# RG-LRU pass 3: token scan hand-scheduled (units of 8 tokens, two units of loads in flight, stores never waited), carry fold in double-buffered batches of 32 pairs
# speedup vs baseline: 1.0179x; 1.0083x over previous
; __device__ __forceinline__ void stage_lru3(const Params& P) {
;     ...
;         for (int it = gw; it < NCH * 8; it += ngw) {
;             const int c = it >> 3, h = it & 7, ch = h * 64 + lane;
;             const float* CHA = (const float*)(ws + OFF_CHA); const float* CHB = (const float*)(ws + OFF_CHB);
;             float hh = 0.f;
; #pragma unroll 1
;             for (int cb = 0; cb < c; cb += 16) {
;                 float ca[16], cbv[16];
; #pragma unroll
;                 for (int i = 0; i < 16; ++i) { const int cc = cb + i < c ? cb + i : c - 1; ca[i] = CHA[(size_t)cc * 512 + ch]; cbv[i] = CHB[(size_t)cc * 512 + ch]; }
; #pragma unroll
;                 for (int i = 0; i < 16; ++i) if (cb + i < c) hh = ca[i] * hh + cbv[i];
;             }
.LBB0_233:
	s_ashr_i32 s8, s2, 3
	s_cmp_lt_i32 s8, 1
	s_cbranch_scc1 .LBB0_237
	s_lshl_b32 s0, s2, 6
	s_and_b32 s0, s0, 0x1c0
	v_or_b32_e32 v0, s0, v8
	s_add_i32 s9, s8, -1
	v_mov_b32_e32 v6, 0
	s_mov_b32 s10, 0
	v_lshlrev_b32_e32 v0, 2, v0
	s_cmp_le_i32 s8, 31
	s_cbranch_scc1 .Lfp_done
	s_add_i32 s1, s10, 0
	s_lshl_b32 s1, s1, 11
	v_add_u32_e32 v198, s1, v0
	global_load_dword v64, v198, s[4:5]
	global_load_dword v128, v198, s[6:7]
	global_load_dword v65, v198, s[4:5] offset:2048
	global_load_dword v129, v198, s[6:7] offset:2048
	v_add_u32_e32 v200, 0x1000, v198
	global_load_dword v66, v200, s[4:5]
	global_load_dword v130, v200, s[6:7]
	global_load_dword v67, v200, s[4:5] offset:2048
	global_load_dword v131, v200, s[6:7] offset:2048
	v_add_u32_e32 v201, 0x2000, v198
	global_load_dword v68, v201, s[4:5]
	global_load_dword v132, v201, s[6:7]
	global_load_dword v69, v201, s[4:5] offset:2048
	global_load_dword v133, v201, s[6:7] offset:2048
	v_add_u32_e32 v199, 0x3000, v198
	global_load_dword v70, v199, s[4:5]
	global_load_dword v134, v199, s[6:7]
	global_load_dword v71, v199, s[4:5] offset:2048
	global_load_dword v135, v199, s[6:7] offset:2048
	v_add_u32_e32 v200, 0x4000, v198
	global_load_dword v72, v200, s[4:5]
	global_load_dword v136, v200, s[6:7]
	global_load_dword v73, v200, s[4:5] offset:2048
	global_load_dword v137, v200, s[6:7] offset:2048
	v_add_u32_e32 v201, 0x5000, v198
	global_load_dword v74, v201, s[4:5]
	global_load_dword v138, v201, s[6:7]
	global_load_dword v75, v201, s[4:5] offset:2048
	global_load_dword v139, v201, s[6:7] offset:2048
	v_add_u32_e32 v199, 0x6000, v198
	global_load_dword v76, v199, s[4:5]
	global_load_dword v140, v199, s[6:7]
	global_load_dword v77, v199, s[4:5] offset:2048
	global_load_dword v141, v199, s[6:7] offset:2048
	v_add_u32_e32 v200, 0x7000, v198
	global_load_dword v78, v200, s[4:5]
	global_load_dword v142, v200, s[6:7]
	global_load_dword v79, v200, s[4:5] offset:2048
	global_load_dword v143, v200, s[6:7] offset:2048
	v_add_u32_e32 v201, 0x8000, v198
	global_load_dword v80, v201, s[4:5]
	global_load_dword v144, v201, s[6:7]
	global_load_dword v81, v201, s[4:5] offset:2048
	global_load_dword v145, v201, s[6:7] offset:2048
	v_add_u32_e32 v199, 0x9000, v198
	global_load_dword v82, v199, s[4:5]
	global_load_dword v146, v199, s[6:7]
	global_load_dword v83, v199, s[4:5] offset:2048
	global_load_dword v147, v199, s[6:7] offset:2048
	v_add_u32_e32 v200, 0xa000, v198
	global_load_dword v84, v200, s[4:5]
	global_load_dword v148, v200, s[6:7]
	global_load_dword v85, v200, s[4:5] offset:2048
	global_load_dword v149, v200, s[6:7] offset:2048
	v_add_u32_e32 v201, 0xb000, v198
	global_load_dword v86, v201, s[4:5]
	global_load_dword v150, v201, s[6:7]
	global_load_dword v87, v201, s[4:5] offset:2048
	global_load_dword v151, v201, s[6:7] offset:2048
	v_add_u32_e32 v199, 0xc000, v198
	global_load_dword v88, v199, s[4:5]
	global_load_dword v152, v199, s[6:7]
	global_load_dword v89, v199, s[4:5] offset:2048
	global_load_dword v158, v199, s[6:7] offset:2048
	v_add_u32_e32 v200, 0xd000, v198
	global_load_dword v90, v200, s[4:5]
	global_load_dword v159, v200, s[6:7]
	global_load_dword v91, v200, s[4:5] offset:2048
	global_load_dword v160, v200, s[6:7] offset:2048
	v_add_u32_e32 v201, 0xe000, v198
	global_load_dword v92, v201, s[4:5]
	global_load_dword v161, v201, s[6:7]
	global_load_dword v93, v201, s[4:5] offset:2048
	global_load_dword v162, v201, s[6:7] offset:2048
	v_add_u32_e32 v199, 0xf000, v198
	global_load_dword v94, v199, s[4:5]
	global_load_dword v163, v199, s[6:7]
	global_load_dword v95, v199, s[4:5] offset:2048
	global_load_dword v164, v199, s[6:7] offset:2048
.Lfp_x:
	s_add_i32 s0, s10, 64
	s_cmp_le_i32 s0, s8
	s_cbranch_scc0 .Lfp_x_last
	s_add_i32 s1, s10, 32
	s_lshl_b32 s1, s1, 11
	v_add_u32_e32 v198, s1, v0
	global_load_dword v96, v198, s[4:5]
	global_load_dword v165, v198, s[6:7]
	global_load_dword v97, v198, s[4:5] offset:2048
	global_load_dword v167, v198, s[6:7] offset:2048
	v_add_u32_e32 v200, 0x1000, v198
	global_load_dword v98, v200, s[4:5]
	global_load_dword v168, v200, s[6:7]
	global_load_dword v99, v200, s[4:5] offset:2048
	global_load_dword v169, v200, s[6:7] offset:2048
	v_add_u32_e32 v201, 0x2000, v198
	global_load_dword v100, v201, s[4:5]
	global_load_dword v170, v201, s[6:7]
	global_load_dword v101, v201, s[4:5] offset:2048
	global_load_dword v171, v201, s[6:7] offset:2048
	v_add_u32_e32 v199, 0x3000, v198
	global_load_dword v102, v199, s[4:5]
	global_load_dword v172, v199, s[6:7]
	global_load_dword v103, v199, s[4:5] offset:2048
	global_load_dword v173, v199, s[6:7] offset:2048
	v_add_u32_e32 v200, 0x4000, v198
	global_load_dword v104, v200, s[4:5]
	global_load_dword v174, v200, s[6:7]
	global_load_dword v105, v200, s[4:5] offset:2048
	global_load_dword v175, v200, s[6:7] offset:2048
	v_add_u32_e32 v201, 0x5000, v198
	global_load_dword v106, v201, s[4:5]
	global_load_dword v176, v201, s[6:7]
	global_load_dword v107, v201, s[4:5] offset:2048
	global_load_dword v177, v201, s[6:7] offset:2048
	v_add_u32_e32 v199, 0x6000, v198
	global_load_dword v108, v199, s[4:5]
	global_load_dword v178, v199, s[6:7]
	global_load_dword v109, v199, s[4:5] offset:2048
	global_load_dword v179, v199, s[6:7] offset:2048
	v_add_u32_e32 v200, 0x7000, v198
	global_load_dword v110, v200, s[4:5]
	global_load_dword v180, v200, s[6:7]
	global_load_dword v111, v200, s[4:5] offset:2048
	global_load_dword v181, v200, s[6:7] offset:2048
	v_add_u32_e32 v201, 0x8000, v198
	global_load_dword v112, v201, s[4:5]
	global_load_dword v182, v201, s[6:7]
	global_load_dword v113, v201, s[4:5] offset:2048
	global_load_dword v183, v201, s[6:7] offset:2048
; __device__ __forceinline__ void stage_lru3(const Params& P) {
;     ...
;             for (int cb = 0; cb < c; cb += 16) {
;                 float ca[16], cbv[16];
; #pragma unroll
;                 for (int i = 0; i < 16; ++i) { const int cc = cb + i < c ? cb + i : c - 1; ca[i] = CHA[(size_t)cc * 512 + ch]; cbv[i] = CHB[(size_t)cc * 512 + ch]; }
; #pragma unroll
;                 for (int i = 0; i < 16; ++i) if (cb + i < c) hh = ca[i] * hh + cbv[i];
;             }
	v_add_u32_e32 v199, 0x9000, v198
	global_load_dword v114, v199, s[4:5]
	global_load_dword v184, v199, s[6:7]
	global_load_dword v115, v199, s[4:5] offset:2048
	global_load_dword v185, v199, s[6:7] offset:2048
	v_add_u32_e32 v200, 0xa000, v198
	global_load_dword v116, v200, s[4:5]
	global_load_dword v186, v200, s[6:7]
	global_load_dword v117, v200, s[4:5] offset:2048
	global_load_dword v187, v200, s[6:7] offset:2048
	v_add_u32_e32 v201, 0xb000, v198
	global_load_dword v118, v201, s[4:5]
	global_load_dword v188, v201, s[6:7]
	global_load_dword v119, v201, s[4:5] offset:2048
	global_load_dword v189, v201, s[6:7] offset:2048
	v_add_u32_e32 v199, 0xc000, v198
	global_load_dword v120, v199, s[4:5]
	global_load_dword v190, v199, s[6:7]
	global_load_dword v121, v199, s[4:5] offset:2048
	global_load_dword v191, v199, s[6:7] offset:2048
	v_add_u32_e32 v200, 0xd000, v198
	global_load_dword v122, v200, s[4:5]
	global_load_dword v192, v200, s[6:7]
	global_load_dword v123, v200, s[4:5] offset:2048
	global_load_dword v193, v200, s[6:7] offset:2048
	v_add_u32_e32 v201, 0xe000, v198
	global_load_dword v124, v201, s[4:5]
	global_load_dword v194, v201, s[6:7]
	global_load_dword v125, v201, s[4:5] offset:2048
	global_load_dword v195, v201, s[6:7] offset:2048
	v_add_u32_e32 v199, 0xf000, v198
	global_load_dword v126, v199, s[4:5]
	global_load_dword v196, v199, s[6:7]
	global_load_dword v127, v199, s[4:5] offset:2048
	global_load_dword v197, v199, s[6:7] offset:2048
	s_waitcnt vmcnt(63)
	v_fmac_f32_e32 v128, v6, v64
	v_fmac_f32_e32 v129, v128, v65
	v_fmac_f32_e32 v130, v129, v66
	v_fmac_f32_e32 v131, v130, v67
	v_fmac_f32_e32 v132, v131, v68
	v_fmac_f32_e32 v133, v132, v69
	v_fmac_f32_e32 v134, v133, v70
	v_fmac_f32_e32 v135, v134, v71
	v_fmac_f32_e32 v136, v135, v72
	v_fmac_f32_e32 v137, v136, v73
	v_fmac_f32_e32 v138, v137, v74
	v_fmac_f32_e32 v139, v138, v75
	v_fmac_f32_e32 v140, v139, v76
	v_fmac_f32_e32 v141, v140, v77
	v_fmac_f32_e32 v142, v141, v78
	v_fmac_f32_e32 v143, v142, v79
	v_fmac_f32_e32 v144, v143, v80
	v_fmac_f32_e32 v145, v144, v81
	v_fmac_f32_e32 v146, v145, v82
	v_fmac_f32_e32 v147, v146, v83
	v_fmac_f32_e32 v148, v147, v84
	v_fmac_f32_e32 v149, v148, v85
	v_fmac_f32_e32 v150, v149, v86
	v_fmac_f32_e32 v151, v150, v87
	v_fmac_f32_e32 v152, v151, v88
	v_fmac_f32_e32 v158, v152, v89
	v_fmac_f32_e32 v159, v158, v90
	v_fmac_f32_e32 v160, v159, v91
	v_fmac_f32_e32 v161, v160, v92
	v_fmac_f32_e32 v162, v161, v93
	v_fmac_f32_e32 v163, v162, v94
	v_fmac_f32_e32 v164, v163, v95
	v_mov_b32_e32 v6, v164
	s_add_i32 s10, s10, 32
	s_branch .Lfp_y
.Lfp_x_last:
	s_waitcnt vmcnt(0)
	v_fmac_f32_e32 v128, v6, v64
	v_fmac_f32_e32 v129, v128, v65
	v_fmac_f32_e32 v130, v129, v66
	v_fmac_f32_e32 v131, v130, v67
	v_fmac_f32_e32 v132, v131, v68
	v_fmac_f32_e32 v133, v132, v69
	v_fmac_f32_e32 v134, v133, v70
	v_fmac_f32_e32 v135, v134, v71
	v_fmac_f32_e32 v136, v135, v72
	v_fmac_f32_e32 v137, v136, v73
	v_fmac_f32_e32 v138, v137, v74
	v_fmac_f32_e32 v139, v138, v75
	v_fmac_f32_e32 v140, v139, v76
	v_fmac_f32_e32 v141, v140, v77
	v_fmac_f32_e32 v142, v141, v78
	v_fmac_f32_e32 v143, v142, v79
	v_fmac_f32_e32 v144, v143, v80
	v_fmac_f32_e32 v145, v144, v81
	v_fmac_f32_e32 v146, v145, v82
	v_fmac_f32_e32 v147, v146, v83
	v_fmac_f32_e32 v148, v147, v84
	v_fmac_f32_e32 v149, v148, v85
	v_fmac_f32_e32 v150, v149, v86
	v_fmac_f32_e32 v151, v150, v87
	v_fmac_f32_e32 v152, v151, v88
	v_fmac_f32_e32 v158, v152, v89
	v_fmac_f32_e32 v159, v158, v90
	v_fmac_f32_e32 v160, v159, v91
	v_fmac_f32_e32 v161, v160, v92
	v_fmac_f32_e32 v162, v161, v93
	v_fmac_f32_e32 v163, v162, v94
	v_fmac_f32_e32 v164, v163, v95
	v_mov_b32_e32 v6, v164
	s_add_i32 s10, s10, 32
	s_branch .Lfp_done
; __device__ __forceinline__ void stage_lru3(const Params& P) {
;     ...
;             for (int cb = 0; cb < c; cb += 16) {
;                 float ca[16], cbv[16];
; #pragma unroll
;                 for (int i = 0; i < 16; ++i) { const int cc = cb + i < c ? cb + i : c - 1; ca[i] = CHA[(size_t)cc * 512 + ch]; cbv[i] = CHB[(size_t)cc * 512 + ch]; }
; #pragma unroll
;                 for (int i = 0; i < 16; ++i) if (cb + i < c) hh = ca[i] * hh + cbv[i];
;             }
.Lfp_y:
	s_add_i32 s0, s10, 64
	s_cmp_le_i32 s0, s8
	s_cbranch_scc0 .Lfp_y_last
	s_add_i32 s1, s10, 32
	s_lshl_b32 s1, s1, 11
	v_add_u32_e32 v198, s1, v0
	global_load_dword v64, v198, s[4:5]
	global_load_dword v128, v198, s[6:7]
	global_load_dword v65, v198, s[4:5] offset:2048
	global_load_dword v129, v198, s[6:7] offset:2048
	v_add_u32_e32 v200, 0x1000, v198
	global_load_dword v66, v200, s[4:5]
	global_load_dword v130, v200, s[6:7]
	global_load_dword v67, v200, s[4:5] offset:2048
	global_load_dword v131, v200, s[6:7] offset:2048
	v_add_u32_e32 v201, 0x2000, v198
	global_load_dword v68, v201, s[4:5]
	global_load_dword v132, v201, s[6:7]
	global_load_dword v69, v201, s[4:5] offset:2048
	global_load_dword v133, v201, s[6:7] offset:2048
	v_add_u32_e32 v199, 0x3000, v198
	global_load_dword v70, v199, s[4:5]
	global_load_dword v134, v199, s[6:7]
	global_load_dword v71, v199, s[4:5] offset:2048
	global_load_dword v135, v199, s[6:7] offset:2048
	v_add_u32_e32 v200, 0x4000, v198
	global_load_dword v72, v200, s[4:5]
	global_load_dword v136, v200, s[6:7]
	global_load_dword v73, v200, s[4:5] offset:2048
	global_load_dword v137, v200, s[6:7] offset:2048
	v_add_u32_e32 v201, 0x5000, v198
	global_load_dword v74, v201, s[4:5]
	global_load_dword v138, v201, s[6:7]
	global_load_dword v75, v201, s[4:5] offset:2048
	global_load_dword v139, v201, s[6:7] offset:2048
	v_add_u32_e32 v199, 0x6000, v198
	global_load_dword v76, v199, s[4:5]
	global_load_dword v140, v199, s[6:7]
	global_load_dword v77, v199, s[4:5] offset:2048
	global_load_dword v141, v199, s[6:7] offset:2048
	v_add_u32_e32 v200, 0x7000, v198
	global_load_dword v78, v200, s[4:5]
	global_load_dword v142, v200, s[6:7]
	global_load_dword v79, v200, s[4:5] offset:2048
	global_load_dword v143, v200, s[6:7] offset:2048
	v_add_u32_e32 v201, 0x8000, v198
	global_load_dword v80, v201, s[4:5]
	global_load_dword v144, v201, s[6:7]
	global_load_dword v81, v201, s[4:5] offset:2048
	global_load_dword v145, v201, s[6:7] offset:2048
	v_add_u32_e32 v199, 0x9000, v198
	global_load_dword v82, v199, s[4:5]
	global_load_dword v146, v199, s[6:7]
	global_load_dword v83, v199, s[4:5] offset:2048
	global_load_dword v147, v199, s[6:7] offset:2048
	v_add_u32_e32 v200, 0xa000, v198
	global_load_dword v84, v200, s[4:5]
	global_load_dword v148, v200, s[6:7]
	global_load_dword v85, v200, s[4:5] offset:2048
	global_load_dword v149, v200, s[6:7] offset:2048
	v_add_u32_e32 v201, 0xb000, v198
	global_load_dword v86, v201, s[4:5]
	global_load_dword v150, v201, s[6:7]
	global_load_dword v87, v201, s[4:5] offset:2048
	global_load_dword v151, v201, s[6:7] offset:2048
	v_add_u32_e32 v199, 0xc000, v198
	global_load_dword v88, v199, s[4:5]
	global_load_dword v152, v199, s[6:7]
	global_load_dword v89, v199, s[4:5] offset:2048
	global_load_dword v158, v199, s[6:7] offset:2048
	v_add_u32_e32 v200, 0xd000, v198
	global_load_dword v90, v200, s[4:5]
	global_load_dword v159, v200, s[6:7]
	global_load_dword v91, v200, s[4:5] offset:2048
	global_load_dword v160, v200, s[6:7] offset:2048
	v_add_u32_e32 v201, 0xe000, v198
	global_load_dword v92, v201, s[4:5]
	global_load_dword v161, v201, s[6:7]
	global_load_dword v93, v201, s[4:5] offset:2048
	global_load_dword v162, v201, s[6:7] offset:2048
	v_add_u32_e32 v199, 0xf000, v198
	global_load_dword v94, v199, s[4:5]
	global_load_dword v163, v199, s[6:7]
	global_load_dword v95, v199, s[4:5] offset:2048
	global_load_dword v164, v199, s[6:7] offset:2048
	s_waitcnt vmcnt(63)
	v_fmac_f32_e32 v165, v6, v96
	v_fmac_f32_e32 v167, v165, v97
	v_fmac_f32_e32 v168, v167, v98
	v_fmac_f32_e32 v169, v168, v99
	v_fmac_f32_e32 v170, v169, v100
	v_fmac_f32_e32 v171, v170, v101
	v_fmac_f32_e32 v172, v171, v102
	v_fmac_f32_e32 v173, v172, v103
	v_fmac_f32_e32 v174, v173, v104
	v_fmac_f32_e32 v175, v174, v105
	v_fmac_f32_e32 v176, v175, v106
	v_fmac_f32_e32 v177, v176, v107
	v_fmac_f32_e32 v178, v177, v108
	v_fmac_f32_e32 v179, v178, v109
	v_fmac_f32_e32 v180, v179, v110
	v_fmac_f32_e32 v181, v180, v111
	v_fmac_f32_e32 v182, v181, v112
	v_fmac_f32_e32 v183, v182, v113
	v_fmac_f32_e32 v184, v183, v114
	v_fmac_f32_e32 v185, v184, v115
	v_fmac_f32_e32 v186, v185, v116
	v_fmac_f32_e32 v187, v186, v117
	v_fmac_f32_e32 v188, v187, v118
	v_fmac_f32_e32 v189, v188, v119
	v_fmac_f32_e32 v190, v189, v120
	v_fmac_f32_e32 v191, v190, v121
	v_fmac_f32_e32 v192, v191, v122
	v_fmac_f32_e32 v193, v192, v123
	v_fmac_f32_e32 v194, v193, v124
	v_fmac_f32_e32 v195, v194, v125
	v_fmac_f32_e32 v196, v195, v126
	v_fmac_f32_e32 v197, v196, v127
	v_mov_b32_e32 v6, v197
	s_add_i32 s10, s10, 32
	s_branch .Lfp_x
.Lfp_y_last:
	s_waitcnt vmcnt(0)
	v_fmac_f32_e32 v165, v6, v96
	v_fmac_f32_e32 v167, v165, v97
	v_fmac_f32_e32 v168, v167, v98
	v_fmac_f32_e32 v169, v168, v99
	v_fmac_f32_e32 v170, v169, v100
	v_fmac_f32_e32 v171, v170, v101
	v_fmac_f32_e32 v172, v171, v102
	v_fmac_f32_e32 v173, v172, v103
	v_fmac_f32_e32 v174, v173, v104
	v_fmac_f32_e32 v175, v174, v105
	v_fmac_f32_e32 v176, v175, v106
	v_fmac_f32_e32 v177, v176, v107
	v_fmac_f32_e32 v178, v177, v108
	v_fmac_f32_e32 v179, v178, v109
	v_fmac_f32_e32 v180, v179, v110
	v_fmac_f32_e32 v181, v180, v111
	v_fmac_f32_e32 v182, v181, v112
	v_fmac_f32_e32 v183, v182, v113
	v_fmac_f32_e32 v184, v183, v114
	v_fmac_f32_e32 v185, v184, v115
	v_fmac_f32_e32 v186, v185, v116
	v_fmac_f32_e32 v187, v186, v117
	v_fmac_f32_e32 v188, v187, v118
	v_fmac_f32_e32 v189, v188, v119
	v_fmac_f32_e32 v190, v189, v120
	v_fmac_f32_e32 v191, v190, v121
	v_fmac_f32_e32 v192, v191, v122
	v_fmac_f32_e32 v193, v192, v123
	v_fmac_f32_e32 v194, v193, v124
	v_fmac_f32_e32 v195, v194, v125
	v_fmac_f32_e32 v196, v195, v126
	v_fmac_f32_e32 v197, v196, v127
	v_mov_b32_e32 v6, v197
	s_add_i32 s10, s10, 32
	s_branch .Lfp_done

; __device__ __forceinline__ float bf2f(bf16 b) { return __uint_as_float(((unsigned)b) << 16); }
; __device__ __forceinline__ unsigned f2bf(float f) { unsigned u = __float_as_uint(f); return (u + 0x7fffu + ((u >> 16) & 1u)) >> 16; }
; __device__ __forceinline__ float frcp(float x) { return __builtin_amdgcn_rcpf(x); }
; __device__ __forceinline__ float gelu_tanh(float x) { const float u = 0.7978845608028654f * (x + 0.044715f * x * x * x); return 0.5f * x * (1.f + tanh_fast(u)); }
; __device__ __forceinline__ float tanh_fast(float x) { return 1.f - 2.f * frcp(1.f + __expf(2.f * x)); }
; __device__ __forceinline__ void stage_lru3(const Params& P) {
;     ...
; #pragma unroll 1
;             for (int tb = c * LCH; tb < (c + 1) * LCH; tb += 16) {
;                 float a_[16], b_[16], g_[16];
; #pragma unroll
;                 for (int i = 0; i < 16; ++i) { a_[i] = LA[(size_t)(tb + i) * 512 + ch]; b_[i] = LBX[(size_t)(tb + i) * 512 + ch]; g_[i] = bf2f(PO[(size_t)(tb + i) * DINO + ch]); }
; #pragma unroll
;                 for (int i = 0; i < 16; ++i) { hh = a_[i] * hh + b_[i]; MIX[(size_t)(tb + i) * D + ch] = (bf16)f2bf(gelu_tanh(g_[i]) * hh); }
;             }
.LBB0_238:
	s_and_b32 s1, s3, 0x1c0
	v_or_b32_e32 v4, s1, v8
	s_lshl_b32 s0, s12, 11
	s_mul_i32 s1, s12, 0xc00
	v_lshl_add_u32 v0, v4, 2, s0
	v_lshl_add_u32 v1, v4, 1, s1
	v_lshl_add_u32 v2, v4, 1, s0
	v_add_u32_e32 v0, 0xb080000, v0
	v_add_u32_e32 v1, 0x8080000, v1
	v_add_u32_e32 v2, 0xf200000, v2
	v_add_u32_e32 v10, 0x0, v0
	v_add_u32_e32 v14, 0x2000000, v0
	v_add_u32_e32 v18, 0x0, v1
	v_add_u32_e32 v11, 0x1000, v0
	v_add_u32_e32 v15, 0x2001000, v0
	v_add_u32_e32 v19, 0x1800, v1
	v_add_u32_e32 v12, 0x2000, v0
	v_add_u32_e32 v16, 0x2002000, v0
	v_add_u32_e32 v20, 0x3000, v1
	v_add_u32_e32 v13, 0x3000, v0
	v_add_u32_e32 v17, 0x2003000, v0
	v_add_u32_e32 v21, 0x4800, v1
	global_load_dword v64, v10, s[72:73]
	global_load_dword v72, v14, s[72:73]
	global_load_ushort v80, v18, s[72:73]
	global_load_dword v65, v10, s[72:73] offset:2048
	global_load_dword v73, v14, s[72:73] offset:2048
	global_load_ushort v81, v18, s[72:73] offset:3072
	global_load_dword v66, v11, s[72:73]
	global_load_dword v74, v15, s[72:73]
	global_load_ushort v82, v19, s[72:73]
	global_load_dword v67, v11, s[72:73] offset:2048
	global_load_dword v75, v15, s[72:73] offset:2048
	global_load_ushort v83, v19, s[72:73] offset:3072
	global_load_dword v68, v12, s[72:73]
	global_load_dword v76, v16, s[72:73]
	global_load_ushort v84, v20, s[72:73]
	global_load_dword v69, v12, s[72:73] offset:2048
	global_load_dword v77, v16, s[72:73] offset:2048
	global_load_ushort v85, v20, s[72:73] offset:3072
	global_load_dword v70, v13, s[72:73]
	global_load_dword v78, v17, s[72:73]
	global_load_ushort v86, v21, s[72:73]
	global_load_dword v71, v13, s[72:73] offset:2048
	global_load_dword v79, v17, s[72:73] offset:2048
	global_load_ushort v87, v21, s[72:73] offset:3072
	v_add_u32_e32 v10, 0x4000, v0
	v_add_u32_e32 v14, 0x2004000, v0
	v_add_u32_e32 v18, 0x6000, v1
	v_add_u32_e32 v11, 0x5000, v0
	v_add_u32_e32 v15, 0x2005000, v0
	v_add_u32_e32 v19, 0x7800, v1
	v_add_u32_e32 v12, 0x6000, v0
	v_add_u32_e32 v16, 0x2006000, v0
	v_add_u32_e32 v20, 0x9000, v1
	v_add_u32_e32 v13, 0x7000, v0
	v_add_u32_e32 v17, 0x2007000, v0
	v_add_u32_e32 v21, 0xa800, v1
	global_load_dword v88, v10, s[72:73]
	global_load_dword v96, v14, s[72:73]
	global_load_ushort v104, v18, s[72:73]
	global_load_dword v89, v10, s[72:73] offset:2048
	global_load_dword v97, v14, s[72:73] offset:2048
	global_load_ushort v105, v18, s[72:73] offset:3072
	global_load_dword v90, v11, s[72:73]
	global_load_dword v98, v15, s[72:73]
	global_load_ushort v106, v19, s[72:73]
	global_load_dword v91, v11, s[72:73] offset:2048
	global_load_dword v99, v15, s[72:73] offset:2048
	global_load_ushort v107, v19, s[72:73] offset:3072
	global_load_dword v92, v12, s[72:73]
	global_load_dword v100, v16, s[72:73]
	global_load_ushort v108, v20, s[72:73]
	global_load_dword v93, v12, s[72:73] offset:2048
	global_load_dword v101, v16, s[72:73] offset:2048
	global_load_ushort v109, v20, s[72:73] offset:3072
	global_load_dword v94, v13, s[72:73]
	global_load_dword v102, v17, s[72:73]
	global_load_ushort v110, v21, s[72:73]
	global_load_dword v95, v13, s[72:73] offset:2048
	global_load_dword v103, v17, s[72:73] offset:2048
	global_load_ushort v111, v21, s[72:73] offset:3072
	s_waitcnt vmcnt(24)
	v_fmac_f32_e32 v72, v6, v64
	v_fmac_f32_e32 v73, v72, v65
	v_fmac_f32_e32 v74, v73, v66
	v_fmac_f32_e32 v75, v74, v67
	v_fmac_f32_e32 v76, v75, v68
	v_fmac_f32_e32 v77, v76, v69
	v_fmac_f32_e32 v78, v77, v70
	v_fmac_f32_e32 v79, v78, v71
	v_lshlrev_b32_e32 v80, 16, v80
	v_lshlrev_b32_e32 v81, 16, v81
	v_lshlrev_b32_e32 v82, 16, v82
	v_lshlrev_b32_e32 v83, 16, v83
	v_lshlrev_b32_e32 v84, 16, v84
	v_lshlrev_b32_e32 v85, 16, v85
	v_lshlrev_b32_e32 v86, 16, v86
	v_lshlrev_b32_e32 v87, 16, v87
	v_mul_f32_e32 v26, 0x3d372713, v80
	v_mul_f32_e32 v27, 0x3d372713, v81
	v_mul_f32_e32 v28, 0x3d372713, v82
	v_mul_f32_e32 v29, 0x3d372713, v83
	v_mul_f32_e32 v30, 0x3d372713, v84
	v_mul_f32_e32 v31, 0x3d372713, v85
	v_mul_f32_e32 v32, 0x3d372713, v86
	v_mul_f32_e32 v33, 0x3d372713, v87
	v_mul_f32_e32 v26, v26, v80
	v_mul_f32_e32 v27, v27, v81
	v_mul_f32_e32 v28, v28, v82
	v_mul_f32_e32 v29, v29, v83
	v_mul_f32_e32 v30, v30, v84
	v_mul_f32_e32 v31, v31, v85
	v_mul_f32_e32 v32, v32, v86
	v_mul_f32_e32 v33, v33, v87
	v_fma_f32 v26, v26, v80, v80
	v_fma_f32 v27, v27, v81, v81
	v_fma_f32 v28, v28, v82, v82
	v_fma_f32 v29, v29, v83, v83
	v_fma_f32 v30, v30, v84, v84
	v_fma_f32 v31, v31, v85, v85
	v_fma_f32 v32, v32, v86, v86
	v_fma_f32 v33, v33, v87, v87
	v_mul_f32_e32 v26, 0x3f4c422a, v26
	v_mul_f32_e32 v27, 0x3f4c422a, v27
	v_mul_f32_e32 v28, 0x3f4c422a, v28
	v_mul_f32_e32 v29, 0x3f4c422a, v29
	v_mul_f32_e32 v30, 0x3f4c422a, v30
	v_mul_f32_e32 v31, 0x3f4c422a, v31
	v_mul_f32_e32 v32, 0x3f4c422a, v32
	v_mul_f32_e32 v33, 0x3f4c422a, v33
	v_add_f32_e32 v26, v26, v26
	v_add_f32_e32 v27, v27, v27
	v_add_f32_e32 v28, v28, v28
	v_add_f32_e32 v29, v29, v29
	v_add_f32_e32 v30, v30, v30
	v_add_f32_e32 v31, v31, v31
	v_add_f32_e32 v32, v32, v32
	v_add_f32_e32 v33, v33, v33
	v_mul_f32_e32 v26, 0x3fb8aa3b, v26
	v_mul_f32_e32 v27, 0x3fb8aa3b, v27
	v_mul_f32_e32 v28, 0x3fb8aa3b, v28
	v_mul_f32_e32 v29, 0x3fb8aa3b, v29
	v_mul_f32_e32 v30, 0x3fb8aa3b, v30
	v_mul_f32_e32 v31, 0x3fb8aa3b, v31
	v_mul_f32_e32 v32, 0x3fb8aa3b, v32
	v_mul_f32_e32 v33, 0x3fb8aa3b, v33
	v_exp_f32_e32 v26, v26
	v_exp_f32_e32 v27, v27
	v_exp_f32_e32 v28, v28
	v_exp_f32_e32 v29, v29
	v_exp_f32_e32 v30, v30
	v_exp_f32_e32 v31, v31
	v_exp_f32_e32 v32, v32
	v_exp_f32_e32 v33, v33
	v_mul_f32_e32 v64, 0.5, v80
	v_mul_f32_e32 v65, 0.5, v81
	v_mul_f32_e32 v66, 0.5, v82
	v_mul_f32_e32 v67, 0.5, v83
	v_mul_f32_e32 v68, 0.5, v84
	v_mul_f32_e32 v69, 0.5, v85
; __device__ __forceinline__ float bf2f(bf16 b) { return __uint_as_float(((unsigned)b) << 16); }
; __device__ __forceinline__ unsigned f2bf(float f) { unsigned u = __float_as_uint(f); return (u + 0x7fffu + ((u >> 16) & 1u)) >> 16; }
; __device__ __forceinline__ float frcp(float x) { return __builtin_amdgcn_rcpf(x); }
; __device__ __forceinline__ float gelu_tanh(float x) { const float u = 0.7978845608028654f * (x + 0.044715f * x * x * x); return 0.5f * x * (1.f + tanh_fast(u)); }
; __device__ __forceinline__ float tanh_fast(float x) { return 1.f - 2.f * frcp(1.f + __expf(2.f * x)); }
; __device__ __forceinline__ void stage_lru3(const Params& P) {
;     ...
; #pragma unroll 1
;             for (int tb = c * LCH; tb < (c + 1) * LCH; tb += 16) {
;                 float a_[16], b_[16], g_[16];
; #pragma unroll
;                 for (int i = 0; i < 16; ++i) { a_[i] = LA[(size_t)(tb + i) * 512 + ch]; b_[i] = LBX[(size_t)(tb + i) * 512 + ch]; g_[i] = bf2f(PO[(size_t)(tb + i) * DINO + ch]); }
; #pragma unroll
;                 for (int i = 0; i < 16; ++i) { hh = a_[i] * hh + b_[i]; MIX[(size_t)(tb + i) * D + ch] = (bf16)f2bf(gelu_tanh(g_[i]) * hh); }
;             }
	v_mul_f32_e32 v70, 0.5, v86
	v_mul_f32_e32 v71, 0.5, v87
	v_add_f32_e32 v26, 1.0, v26
	v_add_f32_e32 v27, 1.0, v27
	v_add_f32_e32 v28, 1.0, v28
	v_add_f32_e32 v29, 1.0, v29
	v_add_f32_e32 v30, 1.0, v30
	v_add_f32_e32 v31, 1.0, v31
	v_add_f32_e32 v32, 1.0, v32
	v_add_f32_e32 v33, 1.0, v33
	v_rcp_f32_e32 v26, v26
	v_rcp_f32_e32 v27, v27
	v_rcp_f32_e32 v28, v28
	v_rcp_f32_e32 v29, v29
	v_rcp_f32_e32 v30, v30
	v_rcp_f32_e32 v31, v31
	v_rcp_f32_e32 v32, v32
	v_rcp_f32_e32 v33, v33
	v_add_u32_e32 v22, 0x0, v2
	v_add_u32_e32 v23, 0x1000, v2
	v_add_u32_e32 v24, 0x2000, v2
	v_add_u32_e32 v25, 0x3000, v2
	s_nop 1
	v_fma_f32 v26, v26, -2.0, 1.0
	v_fma_f32 v27, v27, -2.0, 1.0
	v_fma_f32 v28, v28, -2.0, 1.0
	v_fma_f32 v29, v29, -2.0, 1.0
	v_fma_f32 v30, v30, -2.0, 1.0
	v_fma_f32 v31, v31, -2.0, 1.0
	v_fma_f32 v32, v32, -2.0, 1.0
	v_fma_f32 v33, v33, -2.0, 1.0
	v_add_f32_e32 v26, 1.0, v26
	v_add_f32_e32 v27, 1.0, v27
	v_add_f32_e32 v28, 1.0, v28
	v_add_f32_e32 v29, 1.0, v29
	v_add_f32_e32 v30, 1.0, v30
	v_add_f32_e32 v31, 1.0, v31
	v_add_f32_e32 v32, 1.0, v32
	v_add_f32_e32 v33, 1.0, v33
	v_mul_f32_e32 v26, v64, v26
	v_mul_f32_e32 v27, v65, v27
	v_mul_f32_e32 v28, v66, v28
	v_mul_f32_e32 v29, v67, v29
	v_mul_f32_e32 v30, v68, v30
	v_mul_f32_e32 v31, v69, v31
	v_mul_f32_e32 v32, v70, v32
	v_mul_f32_e32 v33, v71, v33
	v_mul_f32_e32 v26, v72, v26
	v_mul_f32_e32 v27, v73, v27
	v_mul_f32_e32 v28, v74, v28
	v_mul_f32_e32 v29, v75, v29
	v_mul_f32_e32 v30, v76, v30
	v_mul_f32_e32 v31, v77, v31
	v_mul_f32_e32 v32, v78, v32
	v_mul_f32_e32 v33, v79, v33
	v_bfe_u32 v80, v26, 16, 1
	v_bfe_u32 v81, v27, 16, 1
	v_bfe_u32 v82, v28, 16, 1
	v_bfe_u32 v83, v29, 16, 1
	v_bfe_u32 v84, v30, 16, 1
	v_bfe_u32 v85, v31, 16, 1
	v_bfe_u32 v86, v32, 16, 1
	v_bfe_u32 v87, v33, 16, 1
	v_add3_u32 v26, v26, v80, s33
	v_add3_u32 v27, v27, v81, s33
	v_add3_u32 v28, v28, v82, s33
	v_add3_u32 v29, v29, v83, s33
	v_add3_u32 v30, v30, v84, s33
	v_add3_u32 v31, v31, v85, s33
	v_add3_u32 v32, v32, v86, s33
	v_add3_u32 v33, v33, v87, s33
	v_mov_b32_e32 v6, v79
	global_store_short_d16_hi v22, v26, s[72:73]
	global_store_short_d16_hi v22, v27, s[72:73] offset:2048
	global_store_short_d16_hi v23, v28, s[72:73]
	global_store_short_d16_hi v23, v29, s[72:73] offset:2048
	global_store_short_d16_hi v24, v30, s[72:73]
	global_store_short_d16_hi v24, v31, s[72:73] offset:2048
	global_store_short_d16_hi v25, v32, s[72:73]
	global_store_short_d16_hi v25, v33, s[72:73] offset:2048
	s_waitcnt vmcnt(39)
	v_add_u32_e32 v10, 0x8000, v0
	v_add_u32_e32 v14, 0x2008000, v0
	v_add_u32_e32 v18, 0xc000, v1
	v_add_u32_e32 v11, 0x9000, v0
	v_add_u32_e32 v15, 0x2009000, v0
	v_add_u32_e32 v19, 0xd800, v1
	v_add_u32_e32 v12, 0xa000, v0
	v_add_u32_e32 v16, 0x200a000, v0
	v_add_u32_e32 v20, 0xf000, v1
	v_add_u32_e32 v13, 0xb000, v0
	v_add_u32_e32 v17, 0x200b000, v0
	v_add_u32_e32 v21, 0x10800, v1
	global_load_dword v112, v10, s[72:73]
	global_load_dword v120, v14, s[72:73]
	global_load_ushort v128, v18, s[72:73]
	global_load_dword v113, v10, s[72:73] offset:2048
	global_load_dword v121, v14, s[72:73] offset:2048
	global_load_ushort v129, v18, s[72:73] offset:3072
	global_load_dword v114, v11, s[72:73]
	global_load_dword v122, v15, s[72:73]
	global_load_ushort v130, v19, s[72:73]
	global_load_dword v115, v11, s[72:73] offset:2048
	global_load_dword v123, v15, s[72:73] offset:2048
	global_load_ushort v131, v19, s[72:73] offset:3072
	global_load_dword v116, v12, s[72:73]
	global_load_dword v124, v16, s[72:73]
	global_load_ushort v132, v20, s[72:73]
	global_load_dword v117, v12, s[72:73] offset:2048
	global_load_dword v125, v16, s[72:73] offset:2048
	global_load_ushort v133, v20, s[72:73] offset:3072
	global_load_dword v118, v13, s[72:73]
	global_load_dword v126, v17, s[72:73]
	global_load_ushort v134, v21, s[72:73]
	global_load_dword v119, v13, s[72:73] offset:2048
	global_load_dword v127, v17, s[72:73] offset:2048
	global_load_ushort v135, v21, s[72:73] offset:3072
	s_waitcnt vmcnt(32)
	v_fmac_f32_e32 v96, v6, v88
	v_fmac_f32_e32 v97, v96, v89
	v_fmac_f32_e32 v98, v97, v90
	v_fmac_f32_e32 v99, v98, v91
	v_fmac_f32_e32 v100, v99, v92
	v_fmac_f32_e32 v101, v100, v93
	v_fmac_f32_e32 v102, v101, v94
	v_fmac_f32_e32 v103, v102, v95
	v_lshlrev_b32_e32 v104, 16, v104
	v_lshlrev_b32_e32 v105, 16, v105
	v_lshlrev_b32_e32 v106, 16, v106
	v_lshlrev_b32_e32 v107, 16, v107
	v_lshlrev_b32_e32 v108, 16, v108
	v_lshlrev_b32_e32 v109, 16, v109
	v_lshlrev_b32_e32 v110, 16, v110
	v_lshlrev_b32_e32 v111, 16, v111
	v_mul_f32_e32 v26, 0x3d372713, v104
	v_mul_f32_e32 v27, 0x3d372713, v105
	v_mul_f32_e32 v28, 0x3d372713, v106
	v_mul_f32_e32 v29, 0x3d372713, v107
	v_mul_f32_e32 v30, 0x3d372713, v108
	v_mul_f32_e32 v31, 0x3d372713, v109
	v_mul_f32_e32 v32, 0x3d372713, v110
	v_mul_f32_e32 v33, 0x3d372713, v111
	v_mul_f32_e32 v26, v26, v104
	v_mul_f32_e32 v27, v27, v105
	v_mul_f32_e32 v28, v28, v106
	v_mul_f32_e32 v29, v29, v107
	v_mul_f32_e32 v30, v30, v108
	v_mul_f32_e32 v31, v31, v109
	v_mul_f32_e32 v32, v32, v110
	v_mul_f32_e32 v33, v33, v111
	v_fma_f32 v26, v26, v104, v104
	v_fma_f32 v27, v27, v105, v105
	v_fma_f32 v28, v28, v106, v106
	v_fma_f32 v29, v29, v107, v107
	v_fma_f32 v30, v30, v108, v108
	v_fma_f32 v31, v31, v109, v109
	v_fma_f32 v32, v32, v110, v110
	v_fma_f32 v33, v33, v111, v111
	v_mul_f32_e32 v26, 0x3f4c422a, v26
	v_mul_f32_e32 v27, 0x3f4c422a, v27
	v_mul_f32_e32 v28, 0x3f4c422a, v28
	v_mul_f32_e32 v29, 0x3f4c422a, v29
	v_mul_f32_e32 v30, 0x3f4c422a, v30
	v_mul_f32_e32 v31, 0x3f4c422a, v31
	v_mul_f32_e32 v32, 0x3f4c422a, v32
	v_mul_f32_e32 v33, 0x3f4c422a, v33
	v_add_f32_e32 v26, v26, v26
	v_add_f32_e32 v27, v27, v27
; __device__ __forceinline__ float bf2f(bf16 b) { return __uint_as_float(((unsigned)b) << 16); }
; __device__ __forceinline__ unsigned f2bf(float f) { unsigned u = __float_as_uint(f); return (u + 0x7fffu + ((u >> 16) & 1u)) >> 16; }
; __device__ __forceinline__ float frcp(float x) { return __builtin_amdgcn_rcpf(x); }
; __device__ __forceinline__ float gelu_tanh(float x) { const float u = 0.7978845608028654f * (x + 0.044715f * x * x * x); return 0.5f * x * (1.f + tanh_fast(u)); }
; __device__ __forceinline__ float tanh_fast(float x) { return 1.f - 2.f * frcp(1.f + __expf(2.f * x)); }
; __device__ __forceinline__ void stage_lru3(const Params& P) {
;     ...
; #pragma unroll 1
;             for (int tb = c * LCH; tb < (c + 1) * LCH; tb += 16) {
;                 float a_[16], b_[16], g_[16];
; #pragma unroll
;                 for (int i = 0; i < 16; ++i) { a_[i] = LA[(size_t)(tb + i) * 512 + ch]; b_[i] = LBX[(size_t)(tb + i) * 512 + ch]; g_[i] = bf2f(PO[(size_t)(tb + i) * DINO + ch]); }
; #pragma unroll
;                 for (int i = 0; i < 16; ++i) { hh = a_[i] * hh + b_[i]; MIX[(size_t)(tb + i) * D + ch] = (bf16)f2bf(gelu_tanh(g_[i]) * hh); }
;             }
	v_add_f32_e32 v28, v28, v28
	v_add_f32_e32 v29, v29, v29
	v_add_f32_e32 v30, v30, v30
	v_add_f32_e32 v31, v31, v31
	v_add_f32_e32 v32, v32, v32
	v_add_f32_e32 v33, v33, v33
	v_mul_f32_e32 v26, 0x3fb8aa3b, v26
	v_mul_f32_e32 v27, 0x3fb8aa3b, v27
	v_mul_f32_e32 v28, 0x3fb8aa3b, v28
	v_mul_f32_e32 v29, 0x3fb8aa3b, v29
	v_mul_f32_e32 v30, 0x3fb8aa3b, v30
	v_mul_f32_e32 v31, 0x3fb8aa3b, v31
	v_mul_f32_e32 v32, 0x3fb8aa3b, v32
	v_mul_f32_e32 v33, 0x3fb8aa3b, v33
	v_exp_f32_e32 v26, v26
	v_exp_f32_e32 v27, v27
	v_exp_f32_e32 v28, v28
	v_exp_f32_e32 v29, v29
	v_exp_f32_e32 v30, v30
	v_exp_f32_e32 v31, v31
	v_exp_f32_e32 v32, v32
	v_exp_f32_e32 v33, v33
	v_mul_f32_e32 v88, 0.5, v104
	v_mul_f32_e32 v89, 0.5, v105
	v_mul_f32_e32 v90, 0.5, v106
	v_mul_f32_e32 v91, 0.5, v107
	v_mul_f32_e32 v92, 0.5, v108
	v_mul_f32_e32 v93, 0.5, v109
	v_mul_f32_e32 v94, 0.5, v110
	v_mul_f32_e32 v95, 0.5, v111
	v_add_f32_e32 v26, 1.0, v26
	v_add_f32_e32 v27, 1.0, v27
	v_add_f32_e32 v28, 1.0, v28
	v_add_f32_e32 v29, 1.0, v29
	v_add_f32_e32 v30, 1.0, v30
	v_add_f32_e32 v31, 1.0, v31
	v_add_f32_e32 v32, 1.0, v32
	v_add_f32_e32 v33, 1.0, v33
	v_rcp_f32_e32 v26, v26
	v_rcp_f32_e32 v27, v27
	v_rcp_f32_e32 v28, v28
	v_rcp_f32_e32 v29, v29
	v_rcp_f32_e32 v30, v30
	v_rcp_f32_e32 v31, v31
	v_rcp_f32_e32 v32, v32
	v_rcp_f32_e32 v33, v33
	v_add_u32_e32 v22, 0x4000, v2
	v_add_u32_e32 v23, 0x5000, v2
	v_add_u32_e32 v24, 0x6000, v2
	v_add_u32_e32 v25, 0x7000, v2
	s_nop 1
	v_fma_f32 v26, v26, -2.0, 1.0
	v_fma_f32 v27, v27, -2.0, 1.0
	v_fma_f32 v28, v28, -2.0, 1.0
	v_fma_f32 v29, v29, -2.0, 1.0
	v_fma_f32 v30, v30, -2.0, 1.0
	v_fma_f32 v31, v31, -2.0, 1.0
	v_fma_f32 v32, v32, -2.0, 1.0
	v_fma_f32 v33, v33, -2.0, 1.0
	v_add_f32_e32 v26, 1.0, v26
	v_add_f32_e32 v27, 1.0, v27
	v_add_f32_e32 v28, 1.0, v28
	v_add_f32_e32 v29, 1.0, v29
	v_add_f32_e32 v30, 1.0, v30
	v_add_f32_e32 v31, 1.0, v31
	v_add_f32_e32 v32, 1.0, v32
	v_add_f32_e32 v33, 1.0, v33
	v_mul_f32_e32 v26, v88, v26
	v_mul_f32_e32 v27, v89, v27
	v_mul_f32_e32 v28, v90, v28
	v_mul_f32_e32 v29, v91, v29
	v_mul_f32_e32 v30, v92, v30
	v_mul_f32_e32 v31, v93, v31
	v_mul_f32_e32 v32, v94, v32
	v_mul_f32_e32 v33, v95, v33
	v_mul_f32_e32 v26, v96, v26
	v_mul_f32_e32 v27, v97, v27
	v_mul_f32_e32 v28, v98, v28
	v_mul_f32_e32 v29, v99, v29
	v_mul_f32_e32 v30, v100, v30
	v_mul_f32_e32 v31, v101, v31
	v_mul_f32_e32 v32, v102, v32
	v_mul_f32_e32 v33, v103, v33
	v_bfe_u32 v104, v26, 16, 1
	v_bfe_u32 v105, v27, 16, 1
	v_bfe_u32 v106, v28, 16, 1
	v_bfe_u32 v107, v29, 16, 1
	v_bfe_u32 v108, v30, 16, 1
	v_bfe_u32 v109, v31, 16, 1
	v_bfe_u32 v110, v32, 16, 1
	v_bfe_u32 v111, v33, 16, 1
	v_add3_u32 v26, v26, v104, s33
	v_add3_u32 v27, v27, v105, s33
	v_add3_u32 v28, v28, v106, s33
	v_add3_u32 v29, v29, v107, s33
	v_add3_u32 v30, v30, v108, s33
	v_add3_u32 v31, v31, v109, s33
	v_add3_u32 v32, v32, v110, s33
	v_add3_u32 v33, v33, v111, s33
	v_mov_b32_e32 v6, v103
	global_store_short_d16_hi v22, v26, s[72:73]
	global_store_short_d16_hi v22, v27, s[72:73] offset:2048
	global_store_short_d16_hi v23, v28, s[72:73]
	global_store_short_d16_hi v23, v29, s[72:73] offset:2048
	global_store_short_d16_hi v24, v30, s[72:73]
	global_store_short_d16_hi v24, v31, s[72:73] offset:2048
	global_store_short_d16_hi v25, v32, s[72:73]
	global_store_short_d16_hi v25, v33, s[72:73] offset:2048
	s_waitcnt vmcnt(39)
	v_add_u32_e32 v10, 0xc000, v0
	v_add_u32_e32 v14, 0x200c000, v0
	v_add_u32_e32 v18, 0x12000, v1
	v_add_u32_e32 v11, 0xd000, v0
	v_add_u32_e32 v15, 0x200d000, v0
	v_add_u32_e32 v19, 0x13800, v1
	v_add_u32_e32 v12, 0xe000, v0
	v_add_u32_e32 v16, 0x200e000, v0
	v_add_u32_e32 v20, 0x15000, v1
	v_add_u32_e32 v13, 0xf000, v0
	v_add_u32_e32 v17, 0x200f000, v0
	v_add_u32_e32 v21, 0x16800, v1
	global_load_dword v64, v10, s[72:73]
	global_load_dword v72, v14, s[72:73]
	global_load_ushort v80, v18, s[72:73]
	global_load_dword v65, v10, s[72:73] offset:2048
	global_load_dword v73, v14, s[72:73] offset:2048
	global_load_ushort v81, v18, s[72:73] offset:3072
	global_load_dword v66, v11, s[72:73]
	global_load_dword v74, v15, s[72:73]
	global_load_ushort v82, v19, s[72:73]
	global_load_dword v67, v11, s[72:73] offset:2048
	global_load_dword v75, v15, s[72:73] offset:2048
	global_load_ushort v83, v19, s[72:73] offset:3072
	global_load_dword v68, v12, s[72:73]
	global_load_dword v76, v16, s[72:73]
	global_load_ushort v84, v20, s[72:73]
	global_load_dword v69, v12, s[72:73] offset:2048
	global_load_dword v77, v16, s[72:73] offset:2048
	global_load_ushort v85, v20, s[72:73] offset:3072
	global_load_dword v70, v13, s[72:73]
	global_load_dword v78, v17, s[72:73]
	global_load_ushort v86, v21, s[72:73]
	global_load_dword v71, v13, s[72:73] offset:2048
	global_load_dword v79, v17, s[72:73] offset:2048
	global_load_ushort v87, v21, s[72:73] offset:3072
	s_waitcnt vmcnt(32)
; __device__ __forceinline__ float bf2f(bf16 b) { return __uint_as_float(((unsigned)b) << 16); }
; __device__ __forceinline__ unsigned f2bf(float f) { unsigned u = __float_as_uint(f); return (u + 0x7fffu + ((u >> 16) & 1u)) >> 16; }
; __device__ __forceinline__ float frcp(float x) { return __builtin_amdgcn_rcpf(x); }
; __device__ __forceinline__ float gelu_tanh(float x) { const float u = 0.7978845608028654f * (x + 0.044715f * x * x * x); return 0.5f * x * (1.f + tanh_fast(u)); }
; __device__ __forceinline__ float tanh_fast(float x) { return 1.f - 2.f * frcp(1.f + __expf(2.f * x)); }
; __device__ __forceinline__ void stage_lru3(const Params& P) {
;     ...
; #pragma unroll 1
;             for (int tb = c * LCH; tb < (c + 1) * LCH; tb += 16) {
;                 float a_[16], b_[16], g_[16];
; #pragma unroll
;                 for (int i = 0; i < 16; ++i) { a_[i] = LA[(size_t)(tb + i) * 512 + ch]; b_[i] = LBX[(size_t)(tb + i) * 512 + ch]; g_[i] = bf2f(PO[(size_t)(tb + i) * DINO + ch]); }
; #pragma unroll
;                 for (int i = 0; i < 16; ++i) { hh = a_[i] * hh + b_[i]; MIX[(size_t)(tb + i) * D + ch] = (bf16)f2bf(gelu_tanh(g_[i]) * hh); }
;             }
	v_fmac_f32_e32 v120, v6, v112
	v_fmac_f32_e32 v121, v120, v113
	v_fmac_f32_e32 v122, v121, v114
	v_fmac_f32_e32 v123, v122, v115
	v_fmac_f32_e32 v124, v123, v116
	v_fmac_f32_e32 v125, v124, v117
	v_fmac_f32_e32 v126, v125, v118
	v_fmac_f32_e32 v127, v126, v119
	v_lshlrev_b32_e32 v128, 16, v128
	v_lshlrev_b32_e32 v129, 16, v129
	v_lshlrev_b32_e32 v130, 16, v130
	v_lshlrev_b32_e32 v131, 16, v131
	v_lshlrev_b32_e32 v132, 16, v132
	v_lshlrev_b32_e32 v133, 16, v133
	v_lshlrev_b32_e32 v134, 16, v134
	v_lshlrev_b32_e32 v135, 16, v135
	v_mul_f32_e32 v26, 0x3d372713, v128
	v_mul_f32_e32 v27, 0x3d372713, v129
	v_mul_f32_e32 v28, 0x3d372713, v130
	v_mul_f32_e32 v29, 0x3d372713, v131
	v_mul_f32_e32 v30, 0x3d372713, v132
	v_mul_f32_e32 v31, 0x3d372713, v133
	v_mul_f32_e32 v32, 0x3d372713, v134
	v_mul_f32_e32 v33, 0x3d372713, v135
	v_mul_f32_e32 v26, v26, v128
	v_mul_f32_e32 v27, v27, v129
	v_mul_f32_e32 v28, v28, v130
	v_mul_f32_e32 v29, v29, v131
	v_mul_f32_e32 v30, v30, v132
	v_mul_f32_e32 v31, v31, v133
	v_mul_f32_e32 v32, v32, v134
	v_mul_f32_e32 v33, v33, v135
	v_fma_f32 v26, v26, v128, v128
	v_fma_f32 v27, v27, v129, v129
	v_fma_f32 v28, v28, v130, v130
	v_fma_f32 v29, v29, v131, v131
	v_fma_f32 v30, v30, v132, v132
	v_fma_f32 v31, v31, v133, v133
	v_fma_f32 v32, v32, v134, v134
	v_fma_f32 v33, v33, v135, v135
	v_mul_f32_e32 v26, 0x3f4c422a, v26
	v_mul_f32_e32 v27, 0x3f4c422a, v27
	v_mul_f32_e32 v28, 0x3f4c422a, v28
	v_mul_f32_e32 v29, 0x3f4c422a, v29
	v_mul_f32_e32 v30, 0x3f4c422a, v30
	v_mul_f32_e32 v31, 0x3f4c422a, v31
	v_mul_f32_e32 v32, 0x3f4c422a, v32
	v_mul_f32_e32 v33, 0x3f4c422a, v33
	v_add_f32_e32 v26, v26, v26
	v_add_f32_e32 v27, v27, v27
	v_add_f32_e32 v28, v28, v28
	v_add_f32_e32 v29, v29, v29
	v_add_f32_e32 v30, v30, v30
	v_add_f32_e32 v31, v31, v31
	v_add_f32_e32 v32, v32, v32
	v_add_f32_e32 v33, v33, v33
	v_mul_f32_e32 v26, 0x3fb8aa3b, v26
	v_mul_f32_e32 v27, 0x3fb8aa3b, v27
	v_mul_f32_e32 v28, 0x3fb8aa3b, v28
	v_mul_f32_e32 v29, 0x3fb8aa3b, v29
	v_mul_f32_e32 v30, 0x3fb8aa3b, v30
	v_mul_f32_e32 v31, 0x3fb8aa3b, v31
	v_mul_f32_e32 v32, 0x3fb8aa3b, v32
	v_mul_f32_e32 v33, 0x3fb8aa3b, v33
	v_exp_f32_e32 v26, v26
	v_exp_f32_e32 v27, v27
	v_exp_f32_e32 v28, v28
	v_exp_f32_e32 v29, v29
	v_exp_f32_e32 v30, v30
	v_exp_f32_e32 v31, v31
	v_exp_f32_e32 v32, v32
	v_exp_f32_e32 v33, v33
	v_mul_f32_e32 v112, 0.5, v128
	v_mul_f32_e32 v113, 0.5, v129
	v_mul_f32_e32 v114, 0.5, v130
	v_mul_f32_e32 v115, 0.5, v131
	v_mul_f32_e32 v116, 0.5, v132
	v_mul_f32_e32 v117, 0.5, v133
	v_mul_f32_e32 v118, 0.5, v134
	v_mul_f32_e32 v119, 0.5, v135
	v_add_f32_e32 v26, 1.0, v26
	v_add_f32_e32 v27, 1.0, v27
	v_add_f32_e32 v28, 1.0, v28
	v_add_f32_e32 v29, 1.0, v29
	v_add_f32_e32 v30, 1.0, v30
	v_add_f32_e32 v31, 1.0, v31
	v_add_f32_e32 v32, 1.0, v32
	v_add_f32_e32 v33, 1.0, v33
	v_rcp_f32_e32 v26, v26
	v_rcp_f32_e32 v27, v27
	v_rcp_f32_e32 v28, v28
	v_rcp_f32_e32 v29, v29
	v_rcp_f32_e32 v30, v30
	v_rcp_f32_e32 v31, v31
	v_rcp_f32_e32 v32, v32
	v_rcp_f32_e32 v33, v33
	v_add_u32_e32 v22, 0x8000, v2
	v_add_u32_e32 v23, 0x9000, v2
	v_add_u32_e32 v24, 0xa000, v2
	v_add_u32_e32 v25, 0xb000, v2
	s_nop 1
	v_fma_f32 v26, v26, -2.0, 1.0
	v_fma_f32 v27, v27, -2.0, 1.0
	v_fma_f32 v28, v28, -2.0, 1.0
	v_fma_f32 v29, v29, -2.0, 1.0
	v_fma_f32 v30, v30, -2.0, 1.0
	v_fma_f32 v31, v31, -2.0, 1.0
	v_fma_f32 v32, v32, -2.0, 1.0
	v_fma_f32 v33, v33, -2.0, 1.0
	v_add_f32_e32 v26, 1.0, v26
	v_add_f32_e32 v27, 1.0, v27
	v_add_f32_e32 v28, 1.0, v28
	v_add_f32_e32 v29, 1.0, v29
	v_add_f32_e32 v30, 1.0, v30
	v_add_f32_e32 v31, 1.0, v31
	v_add_f32_e32 v32, 1.0, v32
	v_add_f32_e32 v33, 1.0, v33
	v_mul_f32_e32 v26, v112, v26
	v_mul_f32_e32 v27, v113, v27
	v_mul_f32_e32 v28, v114, v28
	v_mul_f32_e32 v29, v115, v29
	v_mul_f32_e32 v30, v116, v30
	v_mul_f32_e32 v31, v117, v31
	v_mul_f32_e32 v32, v118, v32
	v_mul_f32_e32 v33, v119, v33
	v_mul_f32_e32 v26, v120, v26
	v_mul_f32_e32 v27, v121, v27
	v_mul_f32_e32 v28, v122, v28
	v_mul_f32_e32 v29, v123, v29
	v_mul_f32_e32 v30, v124, v30
	v_mul_f32_e32 v31, v125, v31
	v_mul_f32_e32 v32, v126, v32
	v_mul_f32_e32 v33, v127, v33
	v_bfe_u32 v128, v26, 16, 1
	v_bfe_u32 v129, v27, 16, 1
	v_bfe_u32 v130, v28, 16, 1
	v_bfe_u32 v131, v29, 16, 1
	v_bfe_u32 v132, v30, 16, 1
	v_bfe_u32 v133, v31, 16, 1
	v_bfe_u32 v134, v32, 16, 1
	v_bfe_u32 v135, v33, 16, 1
	v_add3_u32 v26, v26, v128, s33
	v_add3_u32 v27, v27, v129, s33
	v_add3_u32 v28, v28, v130, s33
	v_add3_u32 v29, v29, v131, s33
	v_add3_u32 v30, v30, v132, s33
	v_add3_u32 v31, v31, v133, s33
	v_add3_u32 v32, v32, v134, s33
	v_add3_u32 v33, v33, v135, s33
	v_mov_b32_e32 v6, v127
	global_store_short_d16_hi v22, v26, s[72:73]
	global_store_short_d16_hi v22, v27, s[72:73] offset:2048
	global_store_short_d16_hi v23, v28, s[72:73]
	global_store_short_d16_hi v23, v29, s[72:73] offset:2048
	global_store_short_d16_hi v24, v30, s[72:73]
	global_store_short_d16_hi v24, v31, s[72:73] offset:2048
	global_store_short_d16_hi v25, v32, s[72:73]
	global_store_short_d16_hi v25, v33, s[72:73] offset:2048
	s_waitcnt vmcnt(39)
; __device__ __forceinline__ float bf2f(bf16 b) { return __uint_as_float(((unsigned)b) << 16); }
; __device__ __forceinline__ unsigned f2bf(float f) { unsigned u = __float_as_uint(f); return (u + 0x7fffu + ((u >> 16) & 1u)) >> 16; }
; __device__ __forceinline__ float frcp(float x) { return __builtin_amdgcn_rcpf(x); }
; __device__ __forceinline__ float gelu_tanh(float x) { const float u = 0.7978845608028654f * (x + 0.044715f * x * x * x); return 0.5f * x * (1.f + tanh_fast(u)); }
; __device__ __forceinline__ float tanh_fast(float x) { return 1.f - 2.f * frcp(1.f + __expf(2.f * x)); }
; __device__ __forceinline__ void stage_lru3(const Params& P) {
;     ...
; #pragma unroll 1
;             for (int tb = c * LCH; tb < (c + 1) * LCH; tb += 16) {
;                 float a_[16], b_[16], g_[16];
; #pragma unroll
;                 for (int i = 0; i < 16; ++i) { a_[i] = LA[(size_t)(tb + i) * 512 + ch]; b_[i] = LBX[(size_t)(tb + i) * 512 + ch]; g_[i] = bf2f(PO[(size_t)(tb + i) * DINO + ch]); }
; #pragma unroll
;                 for (int i = 0; i < 16; ++i) { hh = a_[i] * hh + b_[i]; MIX[(size_t)(tb + i) * D + ch] = (bf16)f2bf(gelu_tanh(g_[i]) * hh); }
;             }
	v_add_u32_e32 v10, 0x10000, v0
	v_add_u32_e32 v14, 0x2010000, v0
	v_add_u32_e32 v18, 0x18000, v1
	v_add_u32_e32 v11, 0x11000, v0
	v_add_u32_e32 v15, 0x2011000, v0
	v_add_u32_e32 v19, 0x19800, v1
	v_add_u32_e32 v12, 0x12000, v0
	v_add_u32_e32 v16, 0x2012000, v0
	v_add_u32_e32 v20, 0x1b000, v1
	v_add_u32_e32 v13, 0x13000, v0
	v_add_u32_e32 v17, 0x2013000, v0
	v_add_u32_e32 v21, 0x1c800, v1
	global_load_dword v88, v10, s[72:73]
	global_load_dword v96, v14, s[72:73]
	global_load_ushort v104, v18, s[72:73]
	global_load_dword v89, v10, s[72:73] offset:2048
	global_load_dword v97, v14, s[72:73] offset:2048
	global_load_ushort v105, v18, s[72:73] offset:3072
	global_load_dword v90, v11, s[72:73]
	global_load_dword v98, v15, s[72:73]
	global_load_ushort v106, v19, s[72:73]
	global_load_dword v91, v11, s[72:73] offset:2048
	global_load_dword v99, v15, s[72:73] offset:2048
	global_load_ushort v107, v19, s[72:73] offset:3072
	global_load_dword v92, v12, s[72:73]
	global_load_dword v100, v16, s[72:73]
	global_load_ushort v108, v20, s[72:73]
	global_load_dword v93, v12, s[72:73] offset:2048
	global_load_dword v101, v16, s[72:73] offset:2048
	global_load_ushort v109, v20, s[72:73] offset:3072
	global_load_dword v94, v13, s[72:73]
	global_load_dword v102, v17, s[72:73]
	global_load_ushort v110, v21, s[72:73]
	global_load_dword v95, v13, s[72:73] offset:2048
	global_load_dword v103, v17, s[72:73] offset:2048
	global_load_ushort v111, v21, s[72:73] offset:3072
	s_waitcnt vmcnt(32)
	v_fmac_f32_e32 v72, v6, v64
	v_fmac_f32_e32 v73, v72, v65
	v_fmac_f32_e32 v74, v73, v66
	v_fmac_f32_e32 v75, v74, v67
	v_fmac_f32_e32 v76, v75, v68
	v_fmac_f32_e32 v77, v76, v69
	v_fmac_f32_e32 v78, v77, v70
	v_fmac_f32_e32 v79, v78, v71
	v_lshlrev_b32_e32 v80, 16, v80
	v_lshlrev_b32_e32 v81, 16, v81
	v_lshlrev_b32_e32 v82, 16, v82
	v_lshlrev_b32_e32 v83, 16, v83
	v_lshlrev_b32_e32 v84, 16, v84
	v_lshlrev_b32_e32 v85, 16, v85
	v_lshlrev_b32_e32 v86, 16, v86
	v_lshlrev_b32_e32 v87, 16, v87
	v_mul_f32_e32 v26, 0x3d372713, v80
	v_mul_f32_e32 v27, 0x3d372713, v81
	v_mul_f32_e32 v28, 0x3d372713, v82
	v_mul_f32_e32 v29, 0x3d372713, v83
	v_mul_f32_e32 v30, 0x3d372713, v84
	v_mul_f32_e32 v31, 0x3d372713, v85
	v_mul_f32_e32 v32, 0x3d372713, v86
	v_mul_f32_e32 v33, 0x3d372713, v87
	v_mul_f32_e32 v26, v26, v80
	v_mul_f32_e32 v27, v27, v81
	v_mul_f32_e32 v28, v28, v82
	v_mul_f32_e32 v29, v29, v83
	v_mul_f32_e32 v30, v30, v84
	v_mul_f32_e32 v31, v31, v85
	v_mul_f32_e32 v32, v32, v86
	v_mul_f32_e32 v33, v33, v87
	v_fma_f32 v26, v26, v80, v80
	v_fma_f32 v27, v27, v81, v81
	v_fma_f32 v28, v28, v82, v82
	v_fma_f32 v29, v29, v83, v83
	v_fma_f32 v30, v30, v84, v84
	v_fma_f32 v31, v31, v85, v85
	v_fma_f32 v32, v32, v86, v86
	v_fma_f32 v33, v33, v87, v87
	v_mul_f32_e32 v26, 0x3f4c422a, v26
	v_mul_f32_e32 v27, 0x3f4c422a, v27
	v_mul_f32_e32 v28, 0x3f4c422a, v28
	v_mul_f32_e32 v29, 0x3f4c422a, v29
	v_mul_f32_e32 v30, 0x3f4c422a, v30
	v_mul_f32_e32 v31, 0x3f4c422a, v31
	v_mul_f32_e32 v32, 0x3f4c422a, v32
	v_mul_f32_e32 v33, 0x3f4c422a, v33
	v_add_f32_e32 v26, v26, v26
	v_add_f32_e32 v27, v27, v27
	v_add_f32_e32 v28, v28, v28
	v_add_f32_e32 v29, v29, v29
	v_add_f32_e32 v30, v30, v30
	v_add_f32_e32 v31, v31, v31
	v_add_f32_e32 v32, v32, v32
	v_add_f32_e32 v33, v33, v33
	v_mul_f32_e32 v26, 0x3fb8aa3b, v26
	v_mul_f32_e32 v27, 0x3fb8aa3b, v27
	v_mul_f32_e32 v28, 0x3fb8aa3b, v28
	v_mul_f32_e32 v29, 0x3fb8aa3b, v29
	v_mul_f32_e32 v30, 0x3fb8aa3b, v30
	v_mul_f32_e32 v31, 0x3fb8aa3b, v31
	v_mul_f32_e32 v32, 0x3fb8aa3b, v32
	v_mul_f32_e32 v33, 0x3fb8aa3b, v33
	v_exp_f32_e32 v26, v26
	v_exp_f32_e32 v27, v27
	v_exp_f32_e32 v28, v28
	v_exp_f32_e32 v29, v29
	v_exp_f32_e32 v30, v30
	v_exp_f32_e32 v31, v31
	v_exp_f32_e32 v32, v32
	v_exp_f32_e32 v33, v33
	v_mul_f32_e32 v64, 0.5, v80
	v_mul_f32_e32 v65, 0.5, v81
	v_mul_f32_e32 v66, 0.5, v82
	v_mul_f32_e32 v67, 0.5, v83
	v_mul_f32_e32 v68, 0.5, v84
	v_mul_f32_e32 v69, 0.5, v85
	v_mul_f32_e32 v70, 0.5, v86
	v_mul_f32_e32 v71, 0.5, v87
	v_add_f32_e32 v26, 1.0, v26
	v_add_f32_e32 v27, 1.0, v27
	v_add_f32_e32 v28, 1.0, v28
	v_add_f32_e32 v29, 1.0, v29
	v_add_f32_e32 v30, 1.0, v30
	v_add_f32_e32 v31, 1.0, v31
	v_add_f32_e32 v32, 1.0, v32
	v_add_f32_e32 v33, 1.0, v33
	v_rcp_f32_e32 v26, v26
	v_rcp_f32_e32 v27, v27
	v_rcp_f32_e32 v28, v28
	v_rcp_f32_e32 v29, v29
	v_rcp_f32_e32 v30, v30
	v_rcp_f32_e32 v31, v31
	v_rcp_f32_e32 v32, v32
	v_rcp_f32_e32 v33, v33
	v_add_u32_e32 v22, 0xc000, v2
	v_add_u32_e32 v23, 0xd000, v2
	v_add_u32_e32 v24, 0xe000, v2
	v_add_u32_e32 v25, 0xf000, v2
	s_nop 1
	v_fma_f32 v26, v26, -2.0, 1.0
	v_fma_f32 v27, v27, -2.0, 1.0
	v_fma_f32 v28, v28, -2.0, 1.0
	v_fma_f32 v29, v29, -2.0, 1.0
	v_fma_f32 v30, v30, -2.0, 1.0
	v_fma_f32 v31, v31, -2.0, 1.0
	v_fma_f32 v32, v32, -2.0, 1.0
	v_fma_f32 v33, v33, -2.0, 1.0
	v_add_f32_e32 v26, 1.0, v26
	v_add_f32_e32 v27, 1.0, v27
	v_add_f32_e32 v28, 1.0, v28
	v_add_f32_e32 v29, 1.0, v29
	v_add_f32_e32 v30, 1.0, v30
	v_add_f32_e32 v31, 1.0, v31
	v_add_f32_e32 v32, 1.0, v32
	v_add_f32_e32 v33, 1.0, v33
	v_mul_f32_e32 v26, v64, v26
	v_mul_f32_e32 v27, v65, v27
	v_mul_f32_e32 v28, v66, v28
	v_mul_f32_e32 v29, v67, v29
	v_mul_f32_e32 v30, v68, v30
	v_mul_f32_e32 v31, v69, v31
	v_mul_f32_e32 v32, v70, v32
	v_mul_f32_e32 v33, v71, v33
	v_mul_f32_e32 v26, v72, v26
	v_mul_f32_e32 v27, v73, v27
	v_mul_f32_e32 v28, v74, v28
	v_mul_f32_e32 v29, v75, v29
	v_mul_f32_e32 v30, v76, v30
	v_mul_f32_e32 v31, v77, v31
	v_mul_f32_e32 v32, v78, v32
	v_mul_f32_e32 v33, v79, v33
	v_bfe_u32 v80, v26, 16, 1
	v_bfe_u32 v81, v27, 16, 1
	v_bfe_u32 v82, v28, 16, 1
	v_bfe_u32 v83, v29, 16, 1
	v_bfe_u32 v84, v30, 16, 1
	v_bfe_u32 v85, v31, 16, 1
	v_bfe_u32 v86, v32, 16, 1
	v_bfe_u32 v87, v33, 16, 1
	v_add3_u32 v26, v26, v80, s33
	v_add3_u32 v27, v27, v81, s33
	v_add3_u32 v28, v28, v82, s33
	v_add3_u32 v29, v29, v83, s33
	v_add3_u32 v30, v30, v84, s33
	v_add3_u32 v31, v31, v85, s33
	v_add3_u32 v32, v32, v86, s33
	v_add3_u32 v33, v33, v87, s33
	v_mov_b32_e32 v6, v79
	global_store_short_d16_hi v22, v26, s[72:73]
	global_store_short_d16_hi v22, v27, s[72:73] offset:2048
	global_store_short_d16_hi v23, v28, s[72:73]
	global_store_short_d16_hi v23, v29, s[72:73] offset:2048
	global_store_short_d16_hi v24, v30, s[72:73]
	global_store_short_d16_hi v24, v31, s[72:73] offset:2048
	global_store_short_d16_hi v25, v32, s[72:73]
	global_store_short_d16_hi v25, v33, s[72:73] offset:2048
	s_waitcnt vmcnt(39)
; __device__ __forceinline__ float bf2f(bf16 b) { return __uint_as_float(((unsigned)b) << 16); }
; __device__ __forceinline__ unsigned f2bf(float f) { unsigned u = __float_as_uint(f); return (u + 0x7fffu + ((u >> 16) & 1u)) >> 16; }
; __device__ __forceinline__ float frcp(float x) { return __builtin_amdgcn_rcpf(x); }
; __device__ __forceinline__ float gelu_tanh(float x) { const float u = 0.7978845608028654f * (x + 0.044715f * x * x * x); return 0.5f * x * (1.f + tanh_fast(u)); }
; __device__ __forceinline__ float tanh_fast(float x) { return 1.f - 2.f * frcp(1.f + __expf(2.f * x)); }
; __device__ __forceinline__ void stage_lru3(const Params& P) {
;     ...
; #pragma unroll 1
;             for (int tb = c * LCH; tb < (c + 1) * LCH; tb += 16) {
;                 float a_[16], b_[16], g_[16];
; #pragma unroll
;                 for (int i = 0; i < 16; ++i) { a_[i] = LA[(size_t)(tb + i) * 512 + ch]; b_[i] = LBX[(size_t)(tb + i) * 512 + ch]; g_[i] = bf2f(PO[(size_t)(tb + i) * DINO + ch]); }
; #pragma unroll
;                 for (int i = 0; i < 16; ++i) { hh = a_[i] * hh + b_[i]; MIX[(size_t)(tb + i) * D + ch] = (bf16)f2bf(gelu_tanh(g_[i]) * hh); }
;             }
	v_add_u32_e32 v10, 0x14000, v0
	v_add_u32_e32 v14, 0x2014000, v0
	v_add_u32_e32 v18, 0x1e000, v1
	v_add_u32_e32 v11, 0x15000, v0
	v_add_u32_e32 v15, 0x2015000, v0
	v_add_u32_e32 v19, 0x1f800, v1
	v_add_u32_e32 v12, 0x16000, v0
	v_add_u32_e32 v16, 0x2016000, v0
	v_add_u32_e32 v20, 0x21000, v1
	v_add_u32_e32 v13, 0x17000, v0
	v_add_u32_e32 v17, 0x2017000, v0
	v_add_u32_e32 v21, 0x22800, v1
	global_load_dword v112, v10, s[72:73]
	global_load_dword v120, v14, s[72:73]
	global_load_ushort v128, v18, s[72:73]
	global_load_dword v113, v10, s[72:73] offset:2048
	global_load_dword v121, v14, s[72:73] offset:2048
	global_load_ushort v129, v18, s[72:73] offset:3072
	global_load_dword v114, v11, s[72:73]
	global_load_dword v122, v15, s[72:73]
	global_load_ushort v130, v19, s[72:73]
	global_load_dword v115, v11, s[72:73] offset:2048
	global_load_dword v123, v15, s[72:73] offset:2048
	global_load_ushort v131, v19, s[72:73] offset:3072
	global_load_dword v116, v12, s[72:73]
	global_load_dword v124, v16, s[72:73]
	global_load_ushort v132, v20, s[72:73]
	global_load_dword v117, v12, s[72:73] offset:2048
	global_load_dword v125, v16, s[72:73] offset:2048
	global_load_ushort v133, v20, s[72:73] offset:3072
	global_load_dword v118, v13, s[72:73]
	global_load_dword v126, v17, s[72:73]
	global_load_ushort v134, v21, s[72:73]
	global_load_dword v119, v13, s[72:73] offset:2048
	global_load_dword v127, v17, s[72:73] offset:2048
	global_load_ushort v135, v21, s[72:73] offset:3072
	s_waitcnt vmcnt(32)
	v_fmac_f32_e32 v96, v6, v88
	v_fmac_f32_e32 v97, v96, v89
	v_fmac_f32_e32 v98, v97, v90
	v_fmac_f32_e32 v99, v98, v91
	v_fmac_f32_e32 v100, v99, v92
	v_fmac_f32_e32 v101, v100, v93
	v_fmac_f32_e32 v102, v101, v94
	v_fmac_f32_e32 v103, v102, v95
	v_lshlrev_b32_e32 v104, 16, v104
	v_lshlrev_b32_e32 v105, 16, v105
	v_lshlrev_b32_e32 v106, 16, v106
	v_lshlrev_b32_e32 v107, 16, v107
	v_lshlrev_b32_e32 v108, 16, v108
	v_lshlrev_b32_e32 v109, 16, v109
	v_lshlrev_b32_e32 v110, 16, v110
	v_lshlrev_b32_e32 v111, 16, v111
	v_mul_f32_e32 v26, 0x3d372713, v104
	v_mul_f32_e32 v27, 0x3d372713, v105
	v_mul_f32_e32 v28, 0x3d372713, v106
	v_mul_f32_e32 v29, 0x3d372713, v107
	v_mul_f32_e32 v30, 0x3d372713, v108
	v_mul_f32_e32 v31, 0x3d372713, v109
	v_mul_f32_e32 v32, 0x3d372713, v110
	v_mul_f32_e32 v33, 0x3d372713, v111
	v_mul_f32_e32 v26, v26, v104
	v_mul_f32_e32 v27, v27, v105
	v_mul_f32_e32 v28, v28, v106
	v_mul_f32_e32 v29, v29, v107
	v_mul_f32_e32 v30, v30, v108
	v_mul_f32_e32 v31, v31, v109
	v_mul_f32_e32 v32, v32, v110
	v_mul_f32_e32 v33, v33, v111
	v_fma_f32 v26, v26, v104, v104
	v_fma_f32 v27, v27, v105, v105
	v_fma_f32 v28, v28, v106, v106
	v_fma_f32 v29, v29, v107, v107
	v_fma_f32 v30, v30, v108, v108
	v_fma_f32 v31, v31, v109, v109
	v_fma_f32 v32, v32, v110, v110
	v_fma_f32 v33, v33, v111, v111
	v_mul_f32_e32 v26, 0x3f4c422a, v26
	v_mul_f32_e32 v27, 0x3f4c422a, v27
	v_mul_f32_e32 v28, 0x3f4c422a, v28
	v_mul_f32_e32 v29, 0x3f4c422a, v29
	v_mul_f32_e32 v30, 0x3f4c422a, v30
	v_mul_f32_e32 v31, 0x3f4c422a, v31
	v_mul_f32_e32 v32, 0x3f4c422a, v32
	v_mul_f32_e32 v33, 0x3f4c422a, v33
	v_add_f32_e32 v26, v26, v26
	v_add_f32_e32 v27, v27, v27
	v_add_f32_e32 v28, v28, v28
	v_add_f32_e32 v29, v29, v29
	v_add_f32_e32 v30, v30, v30
	v_add_f32_e32 v31, v31, v31
	v_add_f32_e32 v32, v32, v32
	v_add_f32_e32 v33, v33, v33
	v_mul_f32_e32 v26, 0x3fb8aa3b, v26
	v_mul_f32_e32 v27, 0x3fb8aa3b, v27
	v_mul_f32_e32 v28, 0x3fb8aa3b, v28
	v_mul_f32_e32 v29, 0x3fb8aa3b, v29
	v_mul_f32_e32 v30, 0x3fb8aa3b, v30
	v_mul_f32_e32 v31, 0x3fb8aa3b, v31
	v_mul_f32_e32 v32, 0x3fb8aa3b, v32
	v_mul_f32_e32 v33, 0x3fb8aa3b, v33
	v_exp_f32_e32 v26, v26
	v_exp_f32_e32 v27, v27
	v_exp_f32_e32 v28, v28
	v_exp_f32_e32 v29, v29
	v_exp_f32_e32 v30, v30
	v_exp_f32_e32 v31, v31
	v_exp_f32_e32 v32, v32
	v_exp_f32_e32 v33, v33
	v_mul_f32_e32 v88, 0.5, v104
	v_mul_f32_e32 v89, 0.5, v105
	v_mul_f32_e32 v90, 0.5, v106
	v_mul_f32_e32 v91, 0.5, v107
	v_mul_f32_e32 v92, 0.5, v108
	v_mul_f32_e32 v93, 0.5, v109
	v_mul_f32_e32 v94, 0.5, v110
	v_mul_f32_e32 v95, 0.5, v111
	v_add_f32_e32 v26, 1.0, v26
	v_add_f32_e32 v27, 1.0, v27
	v_add_f32_e32 v28, 1.0, v28
	v_add_f32_e32 v29, 1.0, v29
	v_add_f32_e32 v30, 1.0, v30
	v_add_f32_e32 v31, 1.0, v31
	v_add_f32_e32 v32, 1.0, v32
	v_add_f32_e32 v33, 1.0, v33
	v_rcp_f32_e32 v26, v26
	v_rcp_f32_e32 v27, v27
	v_rcp_f32_e32 v28, v28
	v_rcp_f32_e32 v29, v29
	v_rcp_f32_e32 v30, v30
	v_rcp_f32_e32 v31, v31
	v_rcp_f32_e32 v32, v32
	v_rcp_f32_e32 v33, v33
	v_add_u32_e32 v22, 0x10000, v2
	v_add_u32_e32 v23, 0x11000, v2
	v_add_u32_e32 v24, 0x12000, v2
	v_add_u32_e32 v25, 0x13000, v2
	s_nop 1
	v_fma_f32 v26, v26, -2.0, 1.0
	v_fma_f32 v27, v27, -2.0, 1.0
	v_fma_f32 v28, v28, -2.0, 1.0
	v_fma_f32 v29, v29, -2.0, 1.0
	v_fma_f32 v30, v30, -2.0, 1.0
	v_fma_f32 v31, v31, -2.0, 1.0
	v_fma_f32 v32, v32, -2.0, 1.0
	v_fma_f32 v33, v33, -2.0, 1.0
	v_add_f32_e32 v26, 1.0, v26
	v_add_f32_e32 v27, 1.0, v27
	v_add_f32_e32 v28, 1.0, v28
	v_add_f32_e32 v29, 1.0, v29
	v_add_f32_e32 v30, 1.0, v30
	v_add_f32_e32 v31, 1.0, v31
	v_add_f32_e32 v32, 1.0, v32
	v_add_f32_e32 v33, 1.0, v33
	v_mul_f32_e32 v26, v88, v26
	v_mul_f32_e32 v27, v89, v27
	v_mul_f32_e32 v28, v90, v28
	v_mul_f32_e32 v29, v91, v29
	v_mul_f32_e32 v30, v92, v30
	v_mul_f32_e32 v31, v93, v31
	v_mul_f32_e32 v32, v94, v32
	v_mul_f32_e32 v33, v95, v33
	v_mul_f32_e32 v26, v96, v26
	v_mul_f32_e32 v27, v97, v27
	v_mul_f32_e32 v28, v98, v28
	v_mul_f32_e32 v29, v99, v29
	v_mul_f32_e32 v30, v100, v30
	v_mul_f32_e32 v31, v101, v31
	v_mul_f32_e32 v32, v102, v32
	v_mul_f32_e32 v33, v103, v33
	v_bfe_u32 v104, v26, 16, 1
	v_bfe_u32 v105, v27, 16, 1
	v_bfe_u32 v106, v28, 16, 1
	v_bfe_u32 v107, v29, 16, 1
	v_bfe_u32 v108, v30, 16, 1
	v_bfe_u32 v109, v31, 16, 1
	v_bfe_u32 v110, v32, 16, 1
	v_bfe_u32 v111, v33, 16, 1
	v_add3_u32 v26, v26, v104, s33
	v_add3_u32 v27, v27, v105, s33
	v_add3_u32 v28, v28, v106, s33
	v_add3_u32 v29, v29, v107, s33
	v_add3_u32 v30, v30, v108, s33
	v_add3_u32 v31, v31, v109, s33
	v_add3_u32 v32, v32, v110, s33
	v_add3_u32 v33, v33, v111, s33
	v_mov_b32_e32 v6, v103
	global_store_short_d16_hi v22, v26, s[72:73]
	global_store_short_d16_hi v22, v27, s[72:73] offset:2048
	global_store_short_d16_hi v23, v28, s[72:73]
	global_store_short_d16_hi v23, v29, s[72:73] offset:2048
	global_store_short_d16_hi v24, v30, s[72:73]
	global_store_short_d16_hi v24, v31, s[72:73] offset:2048
	global_store_short_d16_hi v25, v32, s[72:73]
	global_store_short_d16_hi v25, v33, s[72:73] offset:2048
	s_waitcnt vmcnt(39)
; __device__ __forceinline__ float bf2f(bf16 b) { return __uint_as_float(((unsigned)b) << 16); }
; __device__ __forceinline__ unsigned f2bf(float f) { unsigned u = __float_as_uint(f); return (u + 0x7fffu + ((u >> 16) & 1u)) >> 16; }
; __device__ __forceinline__ float frcp(float x) { return __builtin_amdgcn_rcpf(x); }
; __device__ __forceinline__ float gelu_tanh(float x) { const float u = 0.7978845608028654f * (x + 0.044715f * x * x * x); return 0.5f * x * (1.f + tanh_fast(u)); }
; __device__ __forceinline__ float tanh_fast(float x) { return 1.f - 2.f * frcp(1.f + __expf(2.f * x)); }
; __device__ __forceinline__ void stage_lru3(const Params& P) {
;     ...
; #pragma unroll 1
;             for (int tb = c * LCH; tb < (c + 1) * LCH; tb += 16) {
;                 float a_[16], b_[16], g_[16];
; #pragma unroll
;                 for (int i = 0; i < 16; ++i) { a_[i] = LA[(size_t)(tb + i) * 512 + ch]; b_[i] = LBX[(size_t)(tb + i) * 512 + ch]; g_[i] = bf2f(PO[(size_t)(tb + i) * DINO + ch]); }
; #pragma unroll
;                 for (int i = 0; i < 16; ++i) { hh = a_[i] * hh + b_[i]; MIX[(size_t)(tb + i) * D + ch] = (bf16)f2bf(gelu_tanh(g_[i]) * hh); }
;             }
	v_add_u32_e32 v10, 0x18000, v0
	v_add_u32_e32 v14, 0x2018000, v0
	v_add_u32_e32 v18, 0x24000, v1
	v_add_u32_e32 v11, 0x19000, v0
	v_add_u32_e32 v15, 0x2019000, v0
	v_add_u32_e32 v19, 0x25800, v1
	v_add_u32_e32 v12, 0x1a000, v0
	v_add_u32_e32 v16, 0x201a000, v0
	v_add_u32_e32 v20, 0x27000, v1
	v_add_u32_e32 v13, 0x1b000, v0
	v_add_u32_e32 v17, 0x201b000, v0
	v_add_u32_e32 v21, 0x28800, v1
	global_load_dword v64, v10, s[72:73]
	global_load_dword v72, v14, s[72:73]
	global_load_ushort v80, v18, s[72:73]
	global_load_dword v65, v10, s[72:73] offset:2048
	global_load_dword v73, v14, s[72:73] offset:2048
	global_load_ushort v81, v18, s[72:73] offset:3072
	global_load_dword v66, v11, s[72:73]
	global_load_dword v74, v15, s[72:73]
	global_load_ushort v82, v19, s[72:73]
	global_load_dword v67, v11, s[72:73] offset:2048
	global_load_dword v75, v15, s[72:73] offset:2048
	global_load_ushort v83, v19, s[72:73] offset:3072
	global_load_dword v68, v12, s[72:73]
	global_load_dword v76, v16, s[72:73]
	global_load_ushort v84, v20, s[72:73]
	global_load_dword v69, v12, s[72:73] offset:2048
	global_load_dword v77, v16, s[72:73] offset:2048
	global_load_ushort v85, v20, s[72:73] offset:3072
	global_load_dword v70, v13, s[72:73]
	global_load_dword v78, v17, s[72:73]
	global_load_ushort v86, v21, s[72:73]
	global_load_dword v71, v13, s[72:73] offset:2048
	global_load_dword v79, v17, s[72:73] offset:2048
	global_load_ushort v87, v21, s[72:73] offset:3072
	s_waitcnt vmcnt(32)
	v_fmac_f32_e32 v120, v6, v112
	v_fmac_f32_e32 v121, v120, v113
	v_fmac_f32_e32 v122, v121, v114
	v_fmac_f32_e32 v123, v122, v115
	v_fmac_f32_e32 v124, v123, v116
	v_fmac_f32_e32 v125, v124, v117
	v_fmac_f32_e32 v126, v125, v118
	v_fmac_f32_e32 v127, v126, v119
	v_lshlrev_b32_e32 v128, 16, v128
	v_lshlrev_b32_e32 v129, 16, v129
	v_lshlrev_b32_e32 v130, 16, v130
	v_lshlrev_b32_e32 v131, 16, v131
	v_lshlrev_b32_e32 v132, 16, v132
	v_lshlrev_b32_e32 v133, 16, v133
	v_lshlrev_b32_e32 v134, 16, v134
	v_lshlrev_b32_e32 v135, 16, v135
	v_mul_f32_e32 v26, 0x3d372713, v128
	v_mul_f32_e32 v27, 0x3d372713, v129
	v_mul_f32_e32 v28, 0x3d372713, v130
	v_mul_f32_e32 v29, 0x3d372713, v131
	v_mul_f32_e32 v30, 0x3d372713, v132
	v_mul_f32_e32 v31, 0x3d372713, v133
	v_mul_f32_e32 v32, 0x3d372713, v134
	v_mul_f32_e32 v33, 0x3d372713, v135
	v_mul_f32_e32 v26, v26, v128
	v_mul_f32_e32 v27, v27, v129
	v_mul_f32_e32 v28, v28, v130
	v_mul_f32_e32 v29, v29, v131
	v_mul_f32_e32 v30, v30, v132
	v_mul_f32_e32 v31, v31, v133
	v_mul_f32_e32 v32, v32, v134
	v_mul_f32_e32 v33, v33, v135
	v_fma_f32 v26, v26, v128, v128
	v_fma_f32 v27, v27, v129, v129
	v_fma_f32 v28, v28, v130, v130
	v_fma_f32 v29, v29, v131, v131
	v_fma_f32 v30, v30, v132, v132
	v_fma_f32 v31, v31, v133, v133
	v_fma_f32 v32, v32, v134, v134
	v_fma_f32 v33, v33, v135, v135
	v_mul_f32_e32 v26, 0x3f4c422a, v26
	v_mul_f32_e32 v27, 0x3f4c422a, v27
	v_mul_f32_e32 v28, 0x3f4c422a, v28
	v_mul_f32_e32 v29, 0x3f4c422a, v29
	v_mul_f32_e32 v30, 0x3f4c422a, v30
	v_mul_f32_e32 v31, 0x3f4c422a, v31
	v_mul_f32_e32 v32, 0x3f4c422a, v32
	v_mul_f32_e32 v33, 0x3f4c422a, v33
	v_add_f32_e32 v26, v26, v26
	v_add_f32_e32 v27, v27, v27
	v_add_f32_e32 v28, v28, v28
	v_add_f32_e32 v29, v29, v29
	v_add_f32_e32 v30, v30, v30
	v_add_f32_e32 v31, v31, v31
	v_add_f32_e32 v32, v32, v32
	v_add_f32_e32 v33, v33, v33
	v_mul_f32_e32 v26, 0x3fb8aa3b, v26
	v_mul_f32_e32 v27, 0x3fb8aa3b, v27
	v_mul_f32_e32 v28, 0x3fb8aa3b, v28
	v_mul_f32_e32 v29, 0x3fb8aa3b, v29
	v_mul_f32_e32 v30, 0x3fb8aa3b, v30
	v_mul_f32_e32 v31, 0x3fb8aa3b, v31
	v_mul_f32_e32 v32, 0x3fb8aa3b, v32
	v_mul_f32_e32 v33, 0x3fb8aa3b, v33
	v_exp_f32_e32 v26, v26
	v_exp_f32_e32 v27, v27
	v_exp_f32_e32 v28, v28
	v_exp_f32_e32 v29, v29
	v_exp_f32_e32 v30, v30
	v_exp_f32_e32 v31, v31
	v_exp_f32_e32 v32, v32
	v_exp_f32_e32 v33, v33
	v_mul_f32_e32 v112, 0.5, v128
	v_mul_f32_e32 v113, 0.5, v129
	v_mul_f32_e32 v114, 0.5, v130
	v_mul_f32_e32 v115, 0.5, v131
	v_mul_f32_e32 v116, 0.5, v132
	v_mul_f32_e32 v117, 0.5, v133
	v_mul_f32_e32 v118, 0.5, v134
	v_mul_f32_e32 v119, 0.5, v135
	v_add_f32_e32 v26, 1.0, v26
	v_add_f32_e32 v27, 1.0, v27
	v_add_f32_e32 v28, 1.0, v28
	v_add_f32_e32 v29, 1.0, v29
	v_add_f32_e32 v30, 1.0, v30
	v_add_f32_e32 v31, 1.0, v31
	v_add_f32_e32 v32, 1.0, v32
	v_add_f32_e32 v33, 1.0, v33
	v_rcp_f32_e32 v26, v26
	v_rcp_f32_e32 v27, v27
	v_rcp_f32_e32 v28, v28
	v_rcp_f32_e32 v29, v29
	v_rcp_f32_e32 v30, v30
	v_rcp_f32_e32 v31, v31
	v_rcp_f32_e32 v32, v32
	v_rcp_f32_e32 v33, v33
	v_add_u32_e32 v22, 0x14000, v2
	v_add_u32_e32 v23, 0x15000, v2
	v_add_u32_e32 v24, 0x16000, v2
	v_add_u32_e32 v25, 0x17000, v2
	s_nop 1
	v_fma_f32 v26, v26, -2.0, 1.0
	v_fma_f32 v27, v27, -2.0, 1.0
	v_fma_f32 v28, v28, -2.0, 1.0
	v_fma_f32 v29, v29, -2.0, 1.0
	v_fma_f32 v30, v30, -2.0, 1.0
	v_fma_f32 v31, v31, -2.0, 1.0
	v_fma_f32 v32, v32, -2.0, 1.0
	v_fma_f32 v33, v33, -2.0, 1.0
	v_add_f32_e32 v26, 1.0, v26
	v_add_f32_e32 v27, 1.0, v27
	v_add_f32_e32 v28, 1.0, v28
	v_add_f32_e32 v29, 1.0, v29
	v_add_f32_e32 v30, 1.0, v30
	v_add_f32_e32 v31, 1.0, v31
	v_add_f32_e32 v32, 1.0, v32
	v_add_f32_e32 v33, 1.0, v33
	v_mul_f32_e32 v26, v112, v26
	v_mul_f32_e32 v27, v113, v27
	v_mul_f32_e32 v28, v114, v28
	v_mul_f32_e32 v29, v115, v29
	v_mul_f32_e32 v30, v116, v30
	v_mul_f32_e32 v31, v117, v31
	v_mul_f32_e32 v32, v118, v32
	v_mul_f32_e32 v33, v119, v33
	v_mul_f32_e32 v26, v120, v26
	v_mul_f32_e32 v27, v121, v27
	v_mul_f32_e32 v28, v122, v28
	v_mul_f32_e32 v29, v123, v29
	v_mul_f32_e32 v30, v124, v30
	v_mul_f32_e32 v31, v125, v31
	v_mul_f32_e32 v32, v126, v32
	v_mul_f32_e32 v33, v127, v33
	v_bfe_u32 v128, v26, 16, 1
	v_bfe_u32 v129, v27, 16, 1
	v_bfe_u32 v130, v28, 16, 1
	v_bfe_u32 v131, v29, 16, 1
	v_bfe_u32 v132, v30, 16, 1
	v_bfe_u32 v133, v31, 16, 1
	v_bfe_u32 v134, v32, 16, 1
	v_bfe_u32 v135, v33, 16, 1
	v_add3_u32 v26, v26, v128, s33
	v_add3_u32 v27, v27, v129, s33
	v_add3_u32 v28, v28, v130, s33
	v_add3_u32 v29, v29, v131, s33
	v_add3_u32 v30, v30, v132, s33
	v_add3_u32 v31, v31, v133, s33
	v_add3_u32 v32, v32, v134, s33
	v_add3_u32 v33, v33, v135, s33
	v_mov_b32_e32 v6, v127
	global_store_short_d16_hi v22, v26, s[72:73]
	global_store_short_d16_hi v22, v27, s[72:73] offset:2048
	global_store_short_d16_hi v23, v28, s[72:73]
	global_store_short_d16_hi v23, v29, s[72:73] offset:2048
	global_store_short_d16_hi v24, v30, s[72:73]
	global_store_short_d16_hi v24, v31, s[72:73] offset:2048
	global_store_short_d16_hi v25, v32, s[72:73]
	global_store_short_d16_hi v25, v33, s[72:73] offset:2048
	s_waitcnt vmcnt(39)
; __device__ __forceinline__ float bf2f(bf16 b) { return __uint_as_float(((unsigned)b) << 16); }
; __device__ __forceinline__ unsigned f2bf(float f) { unsigned u = __float_as_uint(f); return (u + 0x7fffu + ((u >> 16) & 1u)) >> 16; }
; __device__ __forceinline__ float gelu_tanh(float x) { const float u = 0.7978845608028654f * (x + 0.044715f * x * x * x); return 0.5f * x * (1.f + tanh_fast(u)); }
; __device__ __forceinline__ void stage_lru3(const Params& P) {
;     ...
;             for (int tb = c * LCH; tb < (c + 1) * LCH; tb += 16) {
;                 float a_[16], b_[16], g_[16];
; #pragma unroll
;                 for (int i = 0; i < 16; ++i) { a_[i] = LA[(size_t)(tb + i) * 512 + ch]; b_[i] = LBX[(size_t)(tb + i) * 512 + ch]; g_[i] = bf2f(PO[(size_t)(tb + i) * DINO + ch]); }
; #pragma unroll
;                 for (int i = 0; i < 16; ++i) { hh = a_[i] * hh + b_[i]; MIX[(size_t)(tb + i) * D + ch] = (bf16)f2bf(gelu_tanh(g_[i]) * hh); }
	v_add_u32_e32 v10, 0x1c000, v0
	v_add_u32_e32 v14, 0x201c000, v0
	v_add_u32_e32 v18, 0x2a000, v1
	v_add_u32_e32 v11, 0x1d000, v0
	v_add_u32_e32 v15, 0x201d000, v0
	v_add_u32_e32 v19, 0x2b800, v1
	v_add_u32_e32 v12, 0x1e000, v0
	v_add_u32_e32 v16, 0x201e000, v0
	v_add_u32_e32 v20, 0x2d000, v1
	v_add_u32_e32 v13, 0x1f000, v0
	v_add_u32_e32 v17, 0x201f000, v0
	v_add_u32_e32 v21, 0x2e800, v1
	global_load_dword v88, v10, s[72:73]
	global_load_dword v96, v14, s[72:73]
	global_load_ushort v104, v18, s[72:73]
	global_load_dword v89, v10, s[72:73] offset:2048
	global_load_dword v97, v14, s[72:73] offset:2048
	global_load_ushort v105, v18, s[72:73] offset:3072
	global_load_dword v90, v11, s[72:73]
	global_load_dword v98, v15, s[72:73]
	global_load_ushort v106, v19, s[72:73]
	global_load_dword v91, v11, s[72:73] offset:2048
	global_load_dword v99, v15, s[72:73] offset:2048
	global_load_ushort v107, v19, s[72:73] offset:3072
	global_load_dword v92, v12, s[72:73]
	global_load_dword v100, v16, s[72:73]
	global_load_ushort v108, v20, s[72:73]
	global_load_dword v93, v12, s[72:73] offset:2048
	global_load_dword v101, v16, s[72:73] offset:2048
	global_load_ushort v109, v20, s[72:73] offset:3072
	global_load_dword v94, v13, s[72:73]
	global_load_dword v102, v17, s[72:73]
	global_load_ushort v110, v21, s[72:73]
	global_load_dword v95, v13, s[72:73] offset:2048
	global_load_dword v103, v17, s[72:73] offset:2048
	global_load_ushort v111, v21, s[72:73] offset:3072
	s_waitcnt vmcnt(32)
	v_fmac_f32_e32 v72, v6, v64
	v_fmac_f32_e32 v73, v72, v65
	v_fmac_f32_e32 v74, v73, v66
	v_fmac_f32_e32 v75, v74, v67
	v_fmac_f32_e32 v76, v75, v68
	v_fmac_f32_e32 v77, v76, v69
	v_fmac_f32_e32 v78, v77, v70
	v_fmac_f32_e32 v79, v78, v71
	v_lshlrev_b32_e32 v80, 16, v80
	v_lshlrev_b32_e32 v81, 16, v81
	v_lshlrev_b32_e32 v82, 16, v82
	v_lshlrev_b32_e32 v83, 16, v83
	v_lshlrev_b32_e32 v84, 16, v84
	v_lshlrev_b32_e32 v85, 16, v85
	v_lshlrev_b32_e32 v86, 16, v86
	v_lshlrev_b32_e32 v87, 16, v87
	v_mul_f32_e32 v26, 0x3d372713, v80
	v_mul_f32_e32 v27, 0x3d372713, v81
	v_mul_f32_e32 v28, 0x3d372713, v82
	v_mul_f32_e32 v29, 0x3d372713, v83
	v_mul_f32_e32 v30, 0x3d372713, v84
	v_mul_f32_e32 v31, 0x3d372713, v85
	v_mul_f32_e32 v32, 0x3d372713, v86
	v_mul_f32_e32 v33, 0x3d372713, v87
	v_mul_f32_e32 v26, v26, v80
	v_mul_f32_e32 v27, v27, v81
	v_mul_f32_e32 v28, v28, v82
	v_mul_f32_e32 v29, v29, v83
	v_mul_f32_e32 v30, v30, v84
	v_mul_f32_e32 v31, v31, v85
	v_mul_f32_e32 v32, v32, v86
	v_mul_f32_e32 v33, v33, v87
	v_fma_f32 v26, v26, v80, v80
	v_fma_f32 v27, v27, v81, v81
	v_fma_f32 v28, v28, v82, v82
	v_fma_f32 v29, v29, v83, v83
	v_fma_f32 v30, v30, v84, v84
	v_fma_f32 v31, v31, v85, v85
	v_fma_f32 v32, v32, v86, v86
	v_fma_f32 v33, v33, v87, v87
	v_mul_f32_e32 v26, 0x3f4c422a, v26
	v_mul_f32_e32 v27, 0x3f4c422a, v27
	v_mul_f32_e32 v28, 0x3f4c422a, v28
	v_mul_f32_e32 v29, 0x3f4c422a, v29
	v_mul_f32_e32 v30, 0x3f4c422a, v30
	v_mul_f32_e32 v31, 0x3f4c422a, v31
	v_mul_f32_e32 v32, 0x3f4c422a, v32
	v_mul_f32_e32 v33, 0x3f4c422a, v33
	v_add_f32_e32 v26, v26, v26
	v_add_f32_e32 v27, v27, v27
	v_add_f32_e32 v28, v28, v28
	v_add_f32_e32 v29, v29, v29
	v_add_f32_e32 v30, v30, v30
	v_add_f32_e32 v31, v31, v31
	v_add_f32_e32 v32, v32, v32
	v_add_f32_e32 v33, v33, v33
	v_mul_f32_e32 v26, 0x3fb8aa3b, v26
	v_mul_f32_e32 v27, 0x3fb8aa3b, v27
	v_mul_f32_e32 v28, 0x3fb8aa3b, v28
	v_mul_f32_e32 v29, 0x3fb8aa3b, v29
	v_mul_f32_e32 v30, 0x3fb8aa3b, v30
	v_mul_f32_e32 v31, 0x3fb8aa3b, v31
	v_mul_f32_e32 v32, 0x3fb8aa3b, v32
	v_mul_f32_e32 v33, 0x3fb8aa3b, v33
	v_exp_f32_e32 v26, v26
	v_exp_f32_e32 v27, v27
	v_exp_f32_e32 v28, v28
	v_exp_f32_e32 v29, v29
	v_exp_f32_e32 v30, v30
	v_exp_f32_e32 v31, v31
	v_exp_f32_e32 v32, v32
	v_exp_f32_e32 v33, v33
	v_mul_f32_e32 v64, 0.5, v80
	v_mul_f32_e32 v65, 0.5, v81
	v_mul_f32_e32 v66, 0.5, v82
	v_mul_f32_e32 v67, 0.5, v83
	v_mul_f32_e32 v68, 0.5, v84
	v_mul_f32_e32 v69, 0.5, v85
	v_mul_f32_e32 v70, 0.5, v86
	v_mul_f32_e32 v71, 0.5, v87
	v_add_f32_e32 v26, 1.0, v26
	v_add_f32_e32 v27, 1.0, v27
	v_add_f32_e32 v28, 1.0, v28
	v_add_f32_e32 v29, 1.0, v29
	v_add_f32_e32 v30, 1.0, v30
	v_add_f32_e32 v31, 1.0, v31
	v_add_f32_e32 v32, 1.0, v32
	v_add_f32_e32 v33, 1.0, v33
	v_rcp_f32_e32 v26, v26
	v_rcp_f32_e32 v27, v27
	v_rcp_f32_e32 v28, v28
	v_rcp_f32_e32 v29, v29
	v_rcp_f32_e32 v30, v30
	v_rcp_f32_e32 v31, v31
	v_rcp_f32_e32 v32, v32
	v_rcp_f32_e32 v33, v33
	v_add_u32_e32 v22, 0x18000, v2
	v_add_u32_e32 v23, 0x19000, v2
	v_add_u32_e32 v24, 0x1a000, v2
	v_add_u32_e32 v25, 0x1b000, v2
	s_nop 1
	v_fma_f32 v26, v26, -2.0, 1.0
	v_fma_f32 v27, v27, -2.0, 1.0
	v_fma_f32 v28, v28, -2.0, 1.0
	v_fma_f32 v29, v29, -2.0, 1.0
	v_fma_f32 v30, v30, -2.0, 1.0
	v_fma_f32 v31, v31, -2.0, 1.0
	v_fma_f32 v32, v32, -2.0, 1.0
	v_fma_f32 v33, v33, -2.0, 1.0
	v_add_f32_e32 v26, 1.0, v26
	v_add_f32_e32 v27, 1.0, v27
	v_add_f32_e32 v28, 1.0, v28
	v_add_f32_e32 v29, 1.0, v29
	v_add_f32_e32 v30, 1.0, v30
	v_add_f32_e32 v31, 1.0, v31
	v_add_f32_e32 v32, 1.0, v32
	v_add_f32_e32 v33, 1.0, v33
	v_mul_f32_e32 v26, v64, v26
	v_mul_f32_e32 v27, v65, v27
	v_mul_f32_e32 v28, v66, v28
	v_mul_f32_e32 v29, v67, v29
	v_mul_f32_e32 v30, v68, v30
	v_mul_f32_e32 v31, v69, v31
	v_mul_f32_e32 v32, v70, v32
	v_mul_f32_e32 v33, v71, v33
	v_mul_f32_e32 v26, v72, v26
	v_mul_f32_e32 v27, v73, v27
	v_mul_f32_e32 v28, v74, v28
	v_mul_f32_e32 v29, v75, v29
	v_mul_f32_e32 v30, v76, v30
	v_mul_f32_e32 v31, v77, v31
	v_mul_f32_e32 v32, v78, v32
	v_mul_f32_e32 v33, v79, v33
	v_bfe_u32 v80, v26, 16, 1
	v_bfe_u32 v81, v27, 16, 1
	v_bfe_u32 v82, v28, 16, 1
	v_bfe_u32 v83, v29, 16, 1
	v_bfe_u32 v84, v30, 16, 1
	v_bfe_u32 v85, v31, 16, 1
	v_bfe_u32 v86, v32, 16, 1
	v_bfe_u32 v87, v33, 16, 1
	v_add3_u32 v26, v26, v80, s33
	v_add3_u32 v27, v27, v81, s33
	v_add3_u32 v28, v28, v82, s33
	v_add3_u32 v29, v29, v83, s33
	v_add3_u32 v30, v30, v84, s33
	v_add3_u32 v31, v31, v85, s33
	v_add3_u32 v32, v32, v86, s33
	v_add3_u32 v33, v33, v87, s33
	v_mov_b32_e32 v6, v79
	global_store_short_d16_hi v22, v26, s[72:73]
	global_store_short_d16_hi v22, v27, s[72:73] offset:2048
	global_store_short_d16_hi v23, v28, s[72:73]
	global_store_short_d16_hi v23, v29, s[72:73] offset:2048
	global_store_short_d16_hi v24, v30, s[72:73]
	global_store_short_d16_hi v24, v31, s[72:73] offset:2048
	global_store_short_d16_hi v25, v32, s[72:73]
	global_store_short_d16_hi v25, v33, s[72:73] offset:2048
	s_waitcnt vmcnt(8)
; __device__ __forceinline__ float bf2f(bf16 b) { return __uint_as_float(((unsigned)b) << 16); }
; __device__ __forceinline__ unsigned f2bf(float f) { unsigned u = __float_as_uint(f); return (u + 0x7fffu + ((u >> 16) & 1u)) >> 16; }
; __device__ __forceinline__ float gelu_tanh(float x) { const float u = 0.7978845608028654f * (x + 0.044715f * x * x * x); return 0.5f * x * (1.f + tanh_fast(u)); }
; __device__ __forceinline__ void stage_lru3(const Params& P) {
;     ...
;             for (int tb = c * LCH; tb < (c + 1) * LCH; tb += 16) {
;                 float a_[16], b_[16], g_[16];
; #pragma unroll
;                 for (int i = 0; i < 16; ++i) { a_[i] = LA[(size_t)(tb + i) * 512 + ch]; b_[i] = LBX[(size_t)(tb + i) * 512 + ch]; g_[i] = bf2f(PO[(size_t)(tb + i) * DINO + ch]); }
; #pragma unroll
;                 for (int i = 0; i < 16; ++i) { hh = a_[i] * hh + b_[i]; MIX[(size_t)(tb + i) * D + ch] = (bf16)f2bf(gelu_tanh(g_[i]) * hh); }
	v_fmac_f32_e32 v96, v6, v88
	v_fmac_f32_e32 v97, v96, v89
	v_fmac_f32_e32 v98, v97, v90
	v_fmac_f32_e32 v99, v98, v91
	v_fmac_f32_e32 v100, v99, v92
	v_fmac_f32_e32 v101, v100, v93
	v_fmac_f32_e32 v102, v101, v94
	v_fmac_f32_e32 v103, v102, v95
	v_lshlrev_b32_e32 v104, 16, v104
	v_lshlrev_b32_e32 v105, 16, v105
	v_lshlrev_b32_e32 v106, 16, v106
	v_lshlrev_b32_e32 v107, 16, v107
	v_lshlrev_b32_e32 v108, 16, v108
	v_lshlrev_b32_e32 v109, 16, v109
	v_lshlrev_b32_e32 v110, 16, v110
	v_lshlrev_b32_e32 v111, 16, v111
	v_mul_f32_e32 v26, 0x3d372713, v104
	v_mul_f32_e32 v27, 0x3d372713, v105
	v_mul_f32_e32 v28, 0x3d372713, v106
	v_mul_f32_e32 v29, 0x3d372713, v107
	v_mul_f32_e32 v30, 0x3d372713, v108
	v_mul_f32_e32 v31, 0x3d372713, v109
	v_mul_f32_e32 v32, 0x3d372713, v110
	v_mul_f32_e32 v33, 0x3d372713, v111
	v_mul_f32_e32 v26, v26, v104
	v_mul_f32_e32 v27, v27, v105
	v_mul_f32_e32 v28, v28, v106
	v_mul_f32_e32 v29, v29, v107
	v_mul_f32_e32 v30, v30, v108
	v_mul_f32_e32 v31, v31, v109
	v_mul_f32_e32 v32, v32, v110
	v_mul_f32_e32 v33, v33, v111
	v_fma_f32 v26, v26, v104, v104
	v_fma_f32 v27, v27, v105, v105
	v_fma_f32 v28, v28, v106, v106
	v_fma_f32 v29, v29, v107, v107
	v_fma_f32 v30, v30, v108, v108
	v_fma_f32 v31, v31, v109, v109
	v_fma_f32 v32, v32, v110, v110
	v_fma_f32 v33, v33, v111, v111
	v_mul_f32_e32 v26, 0x3f4c422a, v26
	v_mul_f32_e32 v27, 0x3f4c422a, v27
	v_mul_f32_e32 v28, 0x3f4c422a, v28
	v_mul_f32_e32 v29, 0x3f4c422a, v29
	v_mul_f32_e32 v30, 0x3f4c422a, v30
	v_mul_f32_e32 v31, 0x3f4c422a, v31
	v_mul_f32_e32 v32, 0x3f4c422a, v32
	v_mul_f32_e32 v33, 0x3f4c422a, v33
	v_add_f32_e32 v26, v26, v26
	v_add_f32_e32 v27, v27, v27
	v_add_f32_e32 v28, v28, v28
	v_add_f32_e32 v29, v29, v29
	v_add_f32_e32 v30, v30, v30
	v_add_f32_e32 v31, v31, v31
	v_add_f32_e32 v32, v32, v32
	v_add_f32_e32 v33, v33, v33
	v_mul_f32_e32 v26, 0x3fb8aa3b, v26
	v_mul_f32_e32 v27, 0x3fb8aa3b, v27
	v_mul_f32_e32 v28, 0x3fb8aa3b, v28
	v_mul_f32_e32 v29, 0x3fb8aa3b, v29
	v_mul_f32_e32 v30, 0x3fb8aa3b, v30
	v_mul_f32_e32 v31, 0x3fb8aa3b, v31
	v_mul_f32_e32 v32, 0x3fb8aa3b, v32
	v_mul_f32_e32 v33, 0x3fb8aa3b, v33
	v_exp_f32_e32 v26, v26
	v_exp_f32_e32 v27, v27
	v_exp_f32_e32 v28, v28
	v_exp_f32_e32 v29, v29
	v_exp_f32_e32 v30, v30
	v_exp_f32_e32 v31, v31
	v_exp_f32_e32 v32, v32
	v_exp_f32_e32 v33, v33
	v_mul_f32_e32 v88, 0.5, v104
	v_mul_f32_e32 v89, 0.5, v105
	v_mul_f32_e32 v90, 0.5, v106
	v_mul_f32_e32 v91, 0.5, v107
	v_mul_f32_e32 v92, 0.5, v108
	v_mul_f32_e32 v93, 0.5, v109
	v_mul_f32_e32 v94, 0.5, v110
	v_mul_f32_e32 v95, 0.5, v111
	v_add_f32_e32 v26, 1.0, v26
	v_add_f32_e32 v27, 1.0, v27
	v_add_f32_e32 v28, 1.0, v28
	v_add_f32_e32 v29, 1.0, v29
	v_add_f32_e32 v30, 1.0, v30
	v_add_f32_e32 v31, 1.0, v31
	v_add_f32_e32 v32, 1.0, v32
	v_add_f32_e32 v33, 1.0, v33
	v_rcp_f32_e32 v26, v26
	v_rcp_f32_e32 v27, v27
	v_rcp_f32_e32 v28, v28
	v_rcp_f32_e32 v29, v29
	v_rcp_f32_e32 v30, v30
	v_rcp_f32_e32 v31, v31
	v_rcp_f32_e32 v32, v32
	v_rcp_f32_e32 v33, v33
	v_add_u32_e32 v22, 0x1c000, v2
	v_add_u32_e32 v23, 0x1d000, v2
	v_add_u32_e32 v24, 0x1e000, v2
	v_add_u32_e32 v25, 0x1f000, v2
	s_nop 1
	v_fma_f32 v26, v26, -2.0, 1.0
	v_fma_f32 v27, v27, -2.0, 1.0
	v_fma_f32 v28, v28, -2.0, 1.0
	v_fma_f32 v29, v29, -2.0, 1.0
	v_fma_f32 v30, v30, -2.0, 1.0
	v_fma_f32 v31, v31, -2.0, 1.0
	v_fma_f32 v32, v32, -2.0, 1.0
	v_fma_f32 v33, v33, -2.0, 1.0
	v_add_f32_e32 v26, 1.0, v26
	v_add_f32_e32 v27, 1.0, v27
	v_add_f32_e32 v28, 1.0, v28
	v_add_f32_e32 v29, 1.0, v29
	v_add_f32_e32 v30, 1.0, v30
	v_add_f32_e32 v31, 1.0, v31
	v_add_f32_e32 v32, 1.0, v32
	v_add_f32_e32 v33, 1.0, v33
	v_mul_f32_e32 v26, v88, v26
	v_mul_f32_e32 v27, v89, v27
	v_mul_f32_e32 v28, v90, v28
	v_mul_f32_e32 v29, v91, v29
	v_mul_f32_e32 v30, v92, v30
	v_mul_f32_e32 v31, v93, v31
	v_mul_f32_e32 v32, v94, v32
	v_mul_f32_e32 v33, v95, v33
	v_mul_f32_e32 v26, v96, v26
	v_mul_f32_e32 v27, v97, v27
	v_mul_f32_e32 v28, v98, v28
	v_mul_f32_e32 v29, v99, v29
	v_mul_f32_e32 v30, v100, v30
	v_mul_f32_e32 v31, v101, v31
	v_mul_f32_e32 v32, v102, v32
	v_mul_f32_e32 v33, v103, v33
	v_bfe_u32 v104, v26, 16, 1
	v_bfe_u32 v105, v27, 16, 1
	v_bfe_u32 v106, v28, 16, 1
	v_bfe_u32 v107, v29, 16, 1
	v_bfe_u32 v108, v30, 16, 1
	v_bfe_u32 v109, v31, 16, 1
	v_bfe_u32 v110, v32, 16, 1
	v_bfe_u32 v111, v33, 16, 1
	v_add3_u32 v26, v26, v104, s33
	v_add3_u32 v27, v27, v105, s33
	v_add3_u32 v28, v28, v106, s33
	v_add3_u32 v29, v29, v107, s33
	v_add3_u32 v30, v30, v108, s33
	v_add3_u32 v31, v31, v109, s33
	v_add3_u32 v32, v32, v110, s33
	v_add3_u32 v33, v33, v111, s33
	v_mov_b32_e32 v6, v103
	global_store_short_d16_hi v22, v26, s[72:73]
	global_store_short_d16_hi v22, v27, s[72:73] offset:2048
	global_store_short_d16_hi v23, v28, s[72:73]
	global_store_short_d16_hi v23, v29, s[72:73] offset:2048
	global_store_short_d16_hi v24, v30, s[72:73]
	global_store_short_d16_hi v24, v31, s[72:73] offset:2048
	global_store_short_d16_hi v25, v32, s[72:73]
	global_store_short_d16_hi v25, v33, s[72:73] offset:2048
	s_branch .LBB0_232
